# P3 QKV/gate epilogue: bf16 row-per-lane stores widened (v_permlane16_swap pairs -> dwordx4, 2 instead of 4 stores per row group)
# speedup vs baseline: 1.0170x; 1.0141x over previous
; __device__ __forceinline__ unsigned cvt_pk_bf16(float lo, float hi) { unsigned r; asm volatile("v_cvt_pk_bf16_f32 %0, %1, %2" : "=v"(r) : "v"(lo), "v"(hi)); return r; }
; __device__ __forceinline__ float sigmoidf_(float x) { return __builtin_amdgcn_rcpf(1.f + __builtin_amdgcn_exp2f(-x * LOG2E)); }
;     __device__ __forceinline__ void operator()(const f32x4 (&acc)[2][2][4][2], const pg8::Unit& u, int wr, int wc, int fr, int fq) const {
;     ...
;         if (u.pn >= 12) {
;             const int col0 = (u.pn - 12) * 256 + wc * 32 + 4 * fq;
; #pragma unroll
;             for (int ai = 0; ai < 2; ++ai)
; #pragma unroll
;                 for (int m = 0; m < 4; ++m) { const int row = row0 + ai * 128 + m * 16; const float rs = __builtin_amdgcn_rsqf(ss[row] * (1.f / DM) + EPS);
; #pragma unroll
;                     for (int bj = 0; bj < 2; ++bj)
; #pragma unroll
;                         for (int n = 0; n < 2; ++n) { const f32x4 a = acc[ai][bj][m][n] * rs; u32x2 w; w.x = cvt_pk_bf16(sigmoidf_(a[0]), sigmoidf_(a[1])); w.y = cvt_pk_bf16(sigmoidf_(a[2]), sigmoidf_(a[3]));
;                             *(u32x2*)(G + (size_t)row * 2048 + col0 + bj * 128 + n * 16) = w; } }
;             return;
.LBB0_605:
	s_and_b64 vcc, exec, s[0:1]
	s_cbranch_vccz .LBB0_722
	v_ashrrev_i32_e32 v167, 31, v166
	v_lshl_add_u64 v[134:135], v[166:167], 2, s[26:27]
	global_load_dword v142, v[134:135], off
	v_lshl_add_u32 v0, s48, 8, v234
	v_lshlrev_b64 v[138:139], 1, v[0:1]
	v_and_b32_e32 v190, 4, v204
	v_mul_u32_u24_e32 v190, 6, v190
	v_add_u32_e32 v138, v138, v190
	v_lshlrev_b64 v[136:137], 12, v[166:167]
	v_lshl_add_u64 v[136:137], s[28:29], 0, v[136:137]
	v_lshl_add_u64 v[136:137], v[136:137], 0, v[138:139]
	v_or_b32_e32 v140, 16, v166
	v_ashrrev_i32_e32 v141, 31, v140
	s_mov_b32 s3, 0x80000
	s_mov_b64 s[0:1], 0x80000
	s_waitcnt vmcnt(0)
	v_fmamk_f32 v0, v142, 0x3a800000, v236
	v_rsq_f32_e32 v0, v0
	v_lshl_add_u64 v[142:143], v[140:141], 2, s[26:27]
	v_pk_mul_f32 v[132:133], v[132:133], v[0:1] op_sel_hi:[1,0]
	v_pk_mul_f32 v[130:131], v[130:131], v[0:1] op_sel_hi:[1,0]
	v_pk_mul_f32 v[118:119], v[118:119], v[0:1] op_sel_hi:[1,0]
	v_pk_mul_f32 v[128:129], v[128:129], v[0:1] op_sel_hi:[1,0]
	v_pk_mul_f32 v[126:127], v[126:127], v[0:1] op_sel_hi:[1,0]
	v_pk_mul_f32 v[124:125], v[124:125], v[0:1] op_sel_hi:[1,0]
	v_pk_mul_f32 v[122:123], v[122:123], v[0:1] op_sel_hi:[1,0]
	v_pk_mul_f32 v[120:121], v[120:121], v[0:1] op_sel_hi:[1,0]
	v_mul_f32_e32 v0, 0xbfb8aa3b, v130
	v_mul_f32_e32 v130, 0xbfb8aa3b, v131
	v_mul_f32_e32 v131, 0xbfb8aa3b, v132
	v_mul_f32_e32 v132, 0xbfb8aa3b, v133
	v_mul_f32_e32 v118, 0xbfb8aa3b, v118
	v_mul_f32_e32 v119, 0xbfb8aa3b, v119
	v_mul_f32_e32 v126, 0xbfb8aa3b, v126
	v_mul_f32_e32 v127, 0xbfb8aa3b, v127
	v_mul_f32_e32 v128, 0xbfb8aa3b, v128
	v_mul_f32_e32 v129, 0xbfb8aa3b, v129
	v_exp_f32_e32 v0, v0
	v_exp_f32_e32 v130, v130
	v_exp_f32_e32 v131, v131
	v_exp_f32_e32 v132, v132
	v_exp_f32_e32 v118, v118
	v_exp_f32_e32 v119, v119
	v_mul_f32_e32 v122, 0xbfb8aa3b, v122
	v_mul_f32_e32 v123, 0xbfb8aa3b, v123
	v_mul_f32_e32 v124, 0xbfb8aa3b, v124
	v_mul_f32_e32 v125, 0xbfb8aa3b, v125
	v_exp_f32_e32 v126, v126
	v_exp_f32_e32 v127, v127
	v_exp_f32_e32 v128, v128
	v_exp_f32_e32 v129, v129
	v_mul_f32_e32 v120, 0xbfb8aa3b, v120
	v_mul_f32_e32 v121, 0xbfb8aa3b, v121
	v_exp_f32_e32 v122, v122
	v_exp_f32_e32 v123, v123
	v_exp_f32_e32 v124, v124
	v_exp_f32_e32 v125, v125
	v_exp_f32_e32 v120, v120
	v_exp_f32_e32 v121, v121
	v_add_f32_e32 v0, 1.0, v0
	v_add_f32_e32 v130, 1.0, v130
	v_add_f32_e32 v131, 1.0, v131
	v_add_f32_e32 v132, 1.0, v132
	v_add_f32_e32 v118, 1.0, v118
	v_add_f32_e32 v119, 1.0, v119
	v_add_f32_e32 v126, 1.0, v126
	v_add_f32_e32 v127, 1.0, v127
	v_add_f32_e32 v128, 1.0, v128
	v_add_f32_e32 v129, 1.0, v129
	v_rcp_f32_e32 v0, v0
	v_rcp_f32_e32 v130, v130
	v_rcp_f32_e32 v131, v131
	v_rcp_f32_e32 v132, v132
	v_rcp_f32_e32 v133, v118
	v_rcp_f32_e32 v144, v119
	v_cvt_pk_bf16_f32 v190, v0, v130
	v_cvt_pk_bf16_f32 v191, v131, v132
	v_add_f32_e32 v122, 1.0, v122
	v_add_f32_e32 v123, 1.0, v123
	v_add_f32_e32 v124, 1.0, v124
	v_add_f32_e32 v125, 1.0, v125
	v_rcp_f32_e32 v126, v126
	v_rcp_f32_e32 v127, v127
	v_rcp_f32_e32 v128, v128
	v_rcp_f32_e32 v129, v129
	v_cvt_pk_bf16_f32 v192, v126, v127
	v_cvt_pk_bf16_f32 v193, v128, v129
	v_add_f32_e32 v120, 1.0, v120
	v_add_f32_e32 v121, 1.0, v121
	v_rcp_f32_e32 v122, v122
	v_rcp_f32_e32 v123, v123
	v_rcp_f32_e32 v124, v124
	v_rcp_f32_e32 v125, v125
	v_cvt_pk_bf16_f32 v194, v122, v123
	v_cvt_pk_bf16_f32 v195, v124, v125
	v_rcp_f32_e32 v120, v120
	v_rcp_f32_e32 v121, v121
	v_cvt_pk_bf16_f32 v196, v133, v144
	v_cvt_pk_bf16_f32 v197, v120, v121
	s_nop 1
	v_permlane16_swap_b32_e32 v190, v192
	v_permlane16_swap_b32_e32 v191, v193
	v_permlane16_swap_b32_e32 v194, v196
	v_permlane16_swap_b32_e32 v195, v197
	global_store_dwordx4 v[136:137], v[190:193], off
	global_store_dwordx4 v[136:137], v[194:197], off offset:256
	global_load_dword v0, v[142:143], off
	v_lshlrev_b64 v[122:123], 12, v[140:141]
	v_lshl_add_u64 v[122:123], s[28:29], 0, v[122:123]
	v_lshl_add_u64 v[122:123], v[122:123], 0, v[138:139]
	v_or_b32_e32 v118, 32, v166
	v_ashrrev_i32_e32 v119, 31, v118
	v_lshl_add_u64 v[120:121], v[118:119], 2, s[26:27]
	s_waitcnt vmcnt(0)
	v_fmamk_f32 v0, v0, 0x3a800000, v236
	v_rsq_f32_e32 v0, v0
	s_nop 0
	v_pk_mul_f32 v[116:117], v[116:117], v[0:1] op_sel_hi:[1,0]
	v_pk_mul_f32 v[114:115], v[114:115], v[0:1] op_sel_hi:[1,0]
	v_pk_mul_f32 v[102:103], v[102:103], v[0:1] op_sel_hi:[1,0]
	v_pk_mul_f32 v[112:113], v[112:113], v[0:1] op_sel_hi:[1,0]
	v_pk_mul_f32 v[110:111], v[110:111], v[0:1] op_sel_hi:[1,0]
	v_pk_mul_f32 v[108:109], v[108:109], v[0:1] op_sel_hi:[1,0]
	v_pk_mul_f32 v[106:107], v[106:107], v[0:1] op_sel_hi:[1,0]
	v_pk_mul_f32 v[104:105], v[104:105], v[0:1] op_sel_hi:[1,0]
	v_mul_f32_e32 v0, 0xbfb8aa3b, v114
	v_mul_f32_e32 v114, 0xbfb8aa3b, v115
	v_mul_f32_e32 v115, 0xbfb8aa3b, v116
	v_mul_f32_e32 v116, 0xbfb8aa3b, v117
	v_mul_f32_e32 v102, 0xbfb8aa3b, v102
	v_mul_f32_e32 v103, 0xbfb8aa3b, v103
	v_mul_f32_e32 v110, 0xbfb8aa3b, v110
	v_mul_f32_e32 v111, 0xbfb8aa3b, v111
	v_mul_f32_e32 v112, 0xbfb8aa3b, v112
	v_mul_f32_e32 v113, 0xbfb8aa3b, v113
	v_exp_f32_e32 v0, v0
	v_exp_f32_e32 v114, v114
	v_exp_f32_e32 v115, v115
	v_exp_f32_e32 v116, v116
	v_exp_f32_e32 v102, v102
	v_exp_f32_e32 v103, v103
	v_mul_f32_e32 v106, 0xbfb8aa3b, v106
	v_mul_f32_e32 v107, 0xbfb8aa3b, v107
	v_mul_f32_e32 v108, 0xbfb8aa3b, v108
	v_mul_f32_e32 v109, 0xbfb8aa3b, v109
	v_exp_f32_e32 v110, v110
	v_exp_f32_e32 v111, v111
	v_exp_f32_e32 v112, v112
	v_exp_f32_e32 v113, v113
	v_mul_f32_e32 v104, 0xbfb8aa3b, v104
	v_mul_f32_e32 v105, 0xbfb8aa3b, v105
	v_exp_f32_e32 v106, v106
	v_exp_f32_e32 v107, v107
	v_exp_f32_e32 v108, v108
	v_exp_f32_e32 v109, v109
	v_exp_f32_e32 v104, v104
	v_exp_f32_e32 v105, v105
	v_add_f32_e32 v0, 1.0, v0
; __device__ __forceinline__ unsigned cvt_pk_bf16(float lo, float hi) { unsigned r; asm volatile("v_cvt_pk_bf16_f32 %0, %1, %2" : "=v"(r) : "v"(lo), "v"(hi)); return r; }
; __device__ __forceinline__ float sigmoidf_(float x) { return __builtin_amdgcn_rcpf(1.f + __builtin_amdgcn_exp2f(-x * LOG2E)); }
;     __device__ __forceinline__ void operator()(const f32x4 (&acc)[2][2][4][2], const pg8::Unit& u, int wr, int wc, int fr, int fq) const {
;     ...
;         if (u.pn >= 12) {
;             const int col0 = (u.pn - 12) * 256 + wc * 32 + 4 * fq;
; #pragma unroll
;             for (int ai = 0; ai < 2; ++ai)
; #pragma unroll
;                 for (int m = 0; m < 4; ++m) { const int row = row0 + ai * 128 + m * 16; const float rs = __builtin_amdgcn_rsqf(ss[row] * (1.f / DM) + EPS);
; #pragma unroll
;                     for (int bj = 0; bj < 2; ++bj)
; #pragma unroll
;                         for (int n = 0; n < 2; ++n) { const f32x4 a = acc[ai][bj][m][n] * rs; u32x2 w; w.x = cvt_pk_bf16(sigmoidf_(a[0]), sigmoidf_(a[1])); w.y = cvt_pk_bf16(sigmoidf_(a[2]), sigmoidf_(a[3]));
;                             *(u32x2*)(G + (size_t)row * 2048 + col0 + bj * 128 + n * 16) = w; } }
;             return;
	v_add_f32_e32 v114, 1.0, v114
	v_add_f32_e32 v115, 1.0, v115
	v_add_f32_e32 v116, 1.0, v116
	v_add_f32_e32 v102, 1.0, v102
	v_add_f32_e32 v103, 1.0, v103
	v_add_f32_e32 v110, 1.0, v110
	v_add_f32_e32 v111, 1.0, v111
	v_add_f32_e32 v112, 1.0, v112
	v_add_f32_e32 v113, 1.0, v113
	v_rcp_f32_e32 v0, v0
	v_rcp_f32_e32 v114, v114
	v_rcp_f32_e32 v115, v115
	v_rcp_f32_e32 v116, v116
	v_rcp_f32_e32 v117, v102
	v_rcp_f32_e32 v124, v103
	v_cvt_pk_bf16_f32 v190, v0, v114
	v_cvt_pk_bf16_f32 v191, v115, v116
	v_add_f32_e32 v106, 1.0, v106
	v_add_f32_e32 v107, 1.0, v107
	v_add_f32_e32 v108, 1.0, v108
	v_add_f32_e32 v109, 1.0, v109
	v_rcp_f32_e32 v110, v110
	v_rcp_f32_e32 v111, v111
	v_rcp_f32_e32 v112, v112
	v_rcp_f32_e32 v113, v113
	v_cvt_pk_bf16_f32 v192, v110, v111
	v_cvt_pk_bf16_f32 v193, v112, v113
	v_add_f32_e32 v104, 1.0, v104
	v_add_f32_e32 v105, 1.0, v105
	v_rcp_f32_e32 v106, v106
	v_rcp_f32_e32 v107, v107
	v_rcp_f32_e32 v108, v108
	v_rcp_f32_e32 v109, v109
	v_cvt_pk_bf16_f32 v194, v106, v107
	v_cvt_pk_bf16_f32 v195, v108, v109
	v_rcp_f32_e32 v104, v104
	v_rcp_f32_e32 v105, v105
	v_cvt_pk_bf16_f32 v196, v117, v124
	v_cvt_pk_bf16_f32 v197, v104, v105
	s_nop 1
	v_permlane16_swap_b32_e32 v190, v192
	v_permlane16_swap_b32_e32 v191, v193
	v_permlane16_swap_b32_e32 v194, v196
	v_permlane16_swap_b32_e32 v195, v197
	global_store_dwordx4 v[122:123], v[190:193], off
	global_store_dwordx4 v[122:123], v[194:197], off offset:256
	global_load_dword v0, v[120:121], off
	v_lshlrev_b64 v[106:107], 12, v[118:119]
	v_lshl_add_u64 v[106:107], s[28:29], 0, v[106:107]
	v_lshl_add_u64 v[106:107], v[106:107], 0, v[138:139]
	v_or_b32_e32 v102, 48, v166
	v_ashrrev_i32_e32 v103, 31, v102
	v_lshl_add_u64 v[104:105], v[102:103], 2, s[26:27]
	s_waitcnt vmcnt(0)
	v_fmamk_f32 v0, v0, 0x3a800000, v236
	v_rsq_f32_e32 v0, v0
	s_nop 0
	v_pk_mul_f32 v[100:101], v[100:101], v[0:1] op_sel_hi:[1,0]
	v_pk_mul_f32 v[98:99], v[98:99], v[0:1] op_sel_hi:[1,0]
	v_pk_mul_f32 v[86:87], v[86:87], v[0:1] op_sel_hi:[1,0]
	v_pk_mul_f32 v[96:97], v[96:97], v[0:1] op_sel_hi:[1,0]
	v_pk_mul_f32 v[94:95], v[94:95], v[0:1] op_sel_hi:[1,0]
	v_pk_mul_f32 v[92:93], v[92:93], v[0:1] op_sel_hi:[1,0]
	v_pk_mul_f32 v[90:91], v[90:91], v[0:1] op_sel_hi:[1,0]
	v_pk_mul_f32 v[88:89], v[88:89], v[0:1] op_sel_hi:[1,0]
	v_mul_f32_e32 v0, 0xbfb8aa3b, v98
	v_mul_f32_e32 v98, 0xbfb8aa3b, v99
	v_mul_f32_e32 v99, 0xbfb8aa3b, v100
	v_mul_f32_e32 v100, 0xbfb8aa3b, v101
	v_mul_f32_e32 v86, 0xbfb8aa3b, v86
	v_mul_f32_e32 v87, 0xbfb8aa3b, v87
	v_mul_f32_e32 v94, 0xbfb8aa3b, v94
	v_mul_f32_e32 v95, 0xbfb8aa3b, v95
	v_mul_f32_e32 v96, 0xbfb8aa3b, v96
	v_mul_f32_e32 v97, 0xbfb8aa3b, v97
	v_exp_f32_e32 v0, v0
	v_exp_f32_e32 v98, v98
	v_exp_f32_e32 v99, v99
	v_exp_f32_e32 v100, v100
	v_exp_f32_e32 v86, v86
	v_exp_f32_e32 v87, v87
	v_mul_f32_e32 v90, 0xbfb8aa3b, v90
	v_mul_f32_e32 v91, 0xbfb8aa3b, v91
	v_mul_f32_e32 v92, 0xbfb8aa3b, v92
	v_mul_f32_e32 v93, 0xbfb8aa3b, v93
	v_exp_f32_e32 v94, v94
	v_exp_f32_e32 v95, v95
	v_exp_f32_e32 v96, v96
	v_exp_f32_e32 v97, v97
	v_mul_f32_e32 v88, 0xbfb8aa3b, v88
	v_mul_f32_e32 v89, 0xbfb8aa3b, v89
	v_exp_f32_e32 v90, v90
	v_exp_f32_e32 v91, v91
	v_exp_f32_e32 v92, v92
	v_exp_f32_e32 v93, v93
	v_exp_f32_e32 v88, v88
	v_exp_f32_e32 v89, v89
	v_add_f32_e32 v0, 1.0, v0
	v_add_f32_e32 v98, 1.0, v98
	v_add_f32_e32 v99, 1.0, v99
	v_add_f32_e32 v100, 1.0, v100
	v_add_f32_e32 v86, 1.0, v86
	v_add_f32_e32 v87, 1.0, v87
	v_add_f32_e32 v94, 1.0, v94
	v_add_f32_e32 v95, 1.0, v95
	v_add_f32_e32 v96, 1.0, v96
	v_add_f32_e32 v97, 1.0, v97
	v_rcp_f32_e32 v0, v0
	v_rcp_f32_e32 v98, v98
	v_rcp_f32_e32 v99, v99
	v_rcp_f32_e32 v100, v100
	v_rcp_f32_e32 v101, v86
	v_rcp_f32_e32 v108, v87
	v_cvt_pk_bf16_f32 v190, v0, v98
	v_cvt_pk_bf16_f32 v191, v99, v100
	v_add_f32_e32 v90, 1.0, v90
	v_add_f32_e32 v91, 1.0, v91
	v_add_f32_e32 v92, 1.0, v92
	v_add_f32_e32 v93, 1.0, v93
	v_rcp_f32_e32 v94, v94
	v_rcp_f32_e32 v95, v95
	v_rcp_f32_e32 v96, v96
	v_rcp_f32_e32 v97, v97
	v_cvt_pk_bf16_f32 v192, v94, v95
	v_cvt_pk_bf16_f32 v193, v96, v97
	v_add_f32_e32 v88, 1.0, v88
	v_add_f32_e32 v89, 1.0, v89
	v_rcp_f32_e32 v90, v90
	v_rcp_f32_e32 v91, v91
	v_rcp_f32_e32 v92, v92
	v_rcp_f32_e32 v93, v93
	v_cvt_pk_bf16_f32 v194, v90, v91
	v_cvt_pk_bf16_f32 v195, v92, v93
	v_rcp_f32_e32 v88, v88
	v_rcp_f32_e32 v89, v89
	v_cvt_pk_bf16_f32 v196, v101, v108
	v_cvt_pk_bf16_f32 v197, v88, v89
	s_nop 1
	v_permlane16_swap_b32_e32 v190, v192
	v_permlane16_swap_b32_e32 v191, v193
	v_permlane16_swap_b32_e32 v194, v196
	v_permlane16_swap_b32_e32 v195, v197
	global_store_dwordx4 v[106:107], v[190:193], off
	global_store_dwordx4 v[106:107], v[194:197], off offset:256
	global_load_dword v0, v[104:105], off
	v_lshlrev_b64 v[86:87], 12, v[102:103]
	v_lshl_add_u64 v[86:87], s[28:29], 0, v[86:87]
	v_lshl_add_u64 v[86:87], v[86:87], 0, v[138:139]
	s_waitcnt vmcnt(0)
; __device__ __forceinline__ unsigned cvt_pk_bf16(float lo, float hi) { unsigned r; asm volatile("v_cvt_pk_bf16_f32 %0, %1, %2" : "=v"(r) : "v"(lo), "v"(hi)); return r; }
; __device__ __forceinline__ float sigmoidf_(float x) { return __builtin_amdgcn_rcpf(1.f + __builtin_amdgcn_exp2f(-x * LOG2E)); }
;     __device__ __forceinline__ void operator()(const f32x4 (&acc)[2][2][4][2], const pg8::Unit& u, int wr, int wc, int fr, int fq) const {
;     ...
;         if (u.pn >= 12) {
;             const int col0 = (u.pn - 12) * 256 + wc * 32 + 4 * fq;
; #pragma unroll
;             for (int ai = 0; ai < 2; ++ai)
; #pragma unroll
;                 for (int m = 0; m < 4; ++m) { const int row = row0 + ai * 128 + m * 16; const float rs = __builtin_amdgcn_rsqf(ss[row] * (1.f / DM) + EPS);
; #pragma unroll
;                     for (int bj = 0; bj < 2; ++bj)
; #pragma unroll
;                         for (int n = 0; n < 2; ++n) { const f32x4 a = acc[ai][bj][m][n] * rs; u32x2 w; w.x = cvt_pk_bf16(sigmoidf_(a[0]), sigmoidf_(a[1])); w.y = cvt_pk_bf16(sigmoidf_(a[2]), sigmoidf_(a[3]));
;                             *(u32x2*)(G + (size_t)row * 2048 + col0 + bj * 128 + n * 16) = w; } }
;             return;
	v_fmamk_f32 v0, v0, 0x3a800000, v236
	v_rsq_f32_e32 v0, v0
	s_nop 0
	v_pk_mul_f32 v[84:85], v[84:85], v[0:1] op_sel_hi:[1,0]
	v_pk_mul_f32 v[82:83], v[82:83], v[0:1] op_sel_hi:[1,0]
	v_pk_mul_f32 v[70:71], v[70:71], v[0:1] op_sel_hi:[1,0]
	v_pk_mul_f32 v[80:81], v[80:81], v[0:1] op_sel_hi:[1,0]
	v_pk_mul_f32 v[78:79], v[78:79], v[0:1] op_sel_hi:[1,0]
	v_pk_mul_f32 v[76:77], v[76:77], v[0:1] op_sel_hi:[1,0]
	v_pk_mul_f32 v[74:75], v[74:75], v[0:1] op_sel_hi:[1,0]
	v_pk_mul_f32 v[72:73], v[72:73], v[0:1] op_sel_hi:[1,0]
	v_mul_f32_e32 v0, 0xbfb8aa3b, v82
	v_mul_f32_e32 v82, 0xbfb8aa3b, v83
	v_mul_f32_e32 v83, 0xbfb8aa3b, v84
	v_mul_f32_e32 v84, 0xbfb8aa3b, v85
	v_mul_f32_e32 v70, 0xbfb8aa3b, v70
	v_mul_f32_e32 v71, 0xbfb8aa3b, v71
	v_mul_f32_e32 v78, 0xbfb8aa3b, v78
	v_mul_f32_e32 v79, 0xbfb8aa3b, v79
	v_mul_f32_e32 v80, 0xbfb8aa3b, v80
	v_mul_f32_e32 v81, 0xbfb8aa3b, v81
	v_exp_f32_e32 v0, v0
	v_exp_f32_e32 v82, v82
	v_exp_f32_e32 v83, v83
	v_exp_f32_e32 v84, v84
	v_exp_f32_e32 v70, v70
	v_exp_f32_e32 v71, v71
	v_mul_f32_e32 v74, 0xbfb8aa3b, v74
	v_mul_f32_e32 v75, 0xbfb8aa3b, v75
	v_mul_f32_e32 v76, 0xbfb8aa3b, v76
	v_mul_f32_e32 v77, 0xbfb8aa3b, v77
	v_exp_f32_e32 v78, v78
	v_exp_f32_e32 v79, v79
	v_exp_f32_e32 v80, v80
	v_exp_f32_e32 v81, v81
	v_mul_f32_e32 v72, 0xbfb8aa3b, v72
	v_mul_f32_e32 v73, 0xbfb8aa3b, v73
	v_exp_f32_e32 v74, v74
	v_exp_f32_e32 v75, v75
	v_exp_f32_e32 v76, v76
	v_exp_f32_e32 v77, v77
	v_exp_f32_e32 v72, v72
	v_exp_f32_e32 v73, v73
	v_add_f32_e32 v0, 1.0, v0
	v_add_f32_e32 v82, 1.0, v82
	v_add_f32_e32 v83, 1.0, v83
	v_add_f32_e32 v84, 1.0, v84
	v_add_f32_e32 v70, 1.0, v70
	v_add_f32_e32 v71, 1.0, v71
	v_add_f32_e32 v78, 1.0, v78
	v_add_f32_e32 v79, 1.0, v79
	v_add_f32_e32 v80, 1.0, v80
	v_add_f32_e32 v81, 1.0, v81
	v_rcp_f32_e32 v0, v0
	v_rcp_f32_e32 v82, v82
	v_rcp_f32_e32 v83, v83
	v_rcp_f32_e32 v84, v84
	v_rcp_f32_e32 v85, v70
	v_rcp_f32_e32 v88, v71
	v_cvt_pk_bf16_f32 v190, v0, v82
	v_cvt_pk_bf16_f32 v191, v83, v84
	v_add_f32_e32 v74, 1.0, v74
	v_add_f32_e32 v75, 1.0, v75
	v_add_f32_e32 v76, 1.0, v76
	v_add_f32_e32 v77, 1.0, v77
	v_rcp_f32_e32 v78, v78
	v_rcp_f32_e32 v79, v79
	v_rcp_f32_e32 v80, v80
	v_rcp_f32_e32 v81, v81
	v_cvt_pk_bf16_f32 v192, v78, v79
	v_cvt_pk_bf16_f32 v193, v80, v81
	v_add_f32_e32 v72, 1.0, v72
	v_add_f32_e32 v73, 1.0, v73
	v_rcp_f32_e32 v74, v74
	v_rcp_f32_e32 v75, v75
	v_rcp_f32_e32 v76, v76
	v_rcp_f32_e32 v77, v77
	v_cvt_pk_bf16_f32 v194, v74, v75
	v_cvt_pk_bf16_f32 v195, v76, v77
	v_rcp_f32_e32 v72, v72
	v_rcp_f32_e32 v73, v73
	v_cvt_pk_bf16_f32 v196, v85, v88
	v_cvt_pk_bf16_f32 v197, v72, v73
	s_nop 1
	v_permlane16_swap_b32_e32 v190, v192
	v_permlane16_swap_b32_e32 v191, v193
	v_permlane16_swap_b32_e32 v194, v196
	v_permlane16_swap_b32_e32 v195, v197
	global_store_dwordx4 v[86:87], v[190:193], off
	global_store_dwordx4 v[86:87], v[194:197], off offset:256
	global_load_dword v0, v[134:135], off offset:512
	v_add_co_u32_e32 v72, vcc, s3, v136
	v_lshl_add_u64 v[70:71], v[136:137], 0, s[0:1]
	s_nop 0
	v_addc_co_u32_e32 v73, vcc, 0, v137, vcc
	s_mov_b32 s3, 0x90000
	s_mov_b64 s[0:1], 0x90000
	s_waitcnt vmcnt(0)
	v_fmamk_f32 v0, v0, 0x3a800000, v236
	v_rsq_f32_e32 v0, v0
	s_nop 0
	v_pk_mul_f32 v[68:69], v[68:69], v[0:1] op_sel_hi:[1,0]
	v_pk_mul_f32 v[66:67], v[66:67], v[0:1] op_sel_hi:[1,0]
	v_pk_mul_f32 v[54:55], v[54:55], v[0:1] op_sel_hi:[1,0]
	v_pk_mul_f32 v[64:65], v[64:65], v[0:1] op_sel_hi:[1,0]
	v_pk_mul_f32 v[62:63], v[62:63], v[0:1] op_sel_hi:[1,0]
	v_pk_mul_f32 v[60:61], v[60:61], v[0:1] op_sel_hi:[1,0]
	v_pk_mul_f32 v[58:59], v[58:59], v[0:1] op_sel_hi:[1,0]
	v_pk_mul_f32 v[56:57], v[56:57], v[0:1] op_sel_hi:[1,0]
	v_mul_f32_e32 v0, 0xbfb8aa3b, v66
	v_mul_f32_e32 v66, 0xbfb8aa3b, v67
	v_mul_f32_e32 v67, 0xbfb8aa3b, v68
	v_mul_f32_e32 v68, 0xbfb8aa3b, v69
	v_mul_f32_e32 v54, 0xbfb8aa3b, v54
	v_mul_f32_e32 v55, 0xbfb8aa3b, v55
	v_mul_f32_e32 v62, 0xbfb8aa3b, v62
	v_mul_f32_e32 v63, 0xbfb8aa3b, v63
	v_mul_f32_e32 v64, 0xbfb8aa3b, v64
	v_mul_f32_e32 v65, 0xbfb8aa3b, v65
	v_exp_f32_e32 v0, v0
	v_exp_f32_e32 v66, v66
	v_exp_f32_e32 v67, v67
	v_exp_f32_e32 v68, v68
	v_exp_f32_e32 v54, v54
	v_exp_f32_e32 v55, v55
	v_mul_f32_e32 v58, 0xbfb8aa3b, v58
	v_mul_f32_e32 v59, 0xbfb8aa3b, v59
	v_mul_f32_e32 v60, 0xbfb8aa3b, v60
	v_mul_f32_e32 v61, 0xbfb8aa3b, v61
	v_exp_f32_e32 v62, v62
	v_exp_f32_e32 v63, v63
	v_exp_f32_e32 v64, v64
	v_exp_f32_e32 v65, v65
	v_mul_f32_e32 v56, 0xbfb8aa3b, v56
	v_mul_f32_e32 v57, 0xbfb8aa3b, v57
	v_exp_f32_e32 v58, v58
	v_exp_f32_e32 v59, v59
	v_exp_f32_e32 v60, v60
	v_exp_f32_e32 v61, v61
	v_exp_f32_e32 v56, v56
	v_exp_f32_e32 v57, v57
	v_add_f32_e32 v0, 1.0, v0
	v_add_f32_e32 v66, 1.0, v66
	v_add_f32_e32 v67, 1.0, v67
	v_add_f32_e32 v68, 1.0, v68
	v_add_f32_e32 v54, 1.0, v54
	v_add_f32_e32 v55, 1.0, v55
	v_add_f32_e32 v62, 1.0, v62
	v_add_f32_e32 v63, 1.0, v63
	v_add_f32_e32 v64, 1.0, v64
	v_add_f32_e32 v65, 1.0, v65
	v_rcp_f32_e32 v0, v0
	v_rcp_f32_e32 v66, v66
	v_rcp_f32_e32 v67, v67
	v_rcp_f32_e32 v68, v68
	v_rcp_f32_e32 v69, v54
	v_rcp_f32_e32 v74, v55
	v_cvt_pk_bf16_f32 v190, v0, v66
	v_cvt_pk_bf16_f32 v191, v67, v68
	v_add_f32_e32 v58, 1.0, v58
	v_add_f32_e32 v59, 1.0, v59
	v_add_f32_e32 v60, 1.0, v60
	v_add_f32_e32 v61, 1.0, v61
	v_rcp_f32_e32 v62, v62
	v_rcp_f32_e32 v63, v63
	v_rcp_f32_e32 v64, v64
	v_rcp_f32_e32 v65, v65
	v_cvt_pk_bf16_f32 v192, v62, v63
	v_cvt_pk_bf16_f32 v193, v64, v65
	v_add_f32_e32 v56, 1.0, v56
	v_add_f32_e32 v57, 1.0, v57
	v_rcp_f32_e32 v58, v58
	v_rcp_f32_e32 v59, v59
	v_rcp_f32_e32 v60, v60
	v_rcp_f32_e32 v61, v61
	v_cvt_pk_bf16_f32 v194, v58, v59
	v_cvt_pk_bf16_f32 v195, v60, v61
	v_rcp_f32_e32 v56, v56
	v_rcp_f32_e32 v57, v57
	v_cvt_pk_bf16_f32 v196, v69, v74
	v_cvt_pk_bf16_f32 v197, v56, v57
	s_nop 1
	v_permlane16_swap_b32_e32 v190, v192
	v_permlane16_swap_b32_e32 v191, v193
	v_permlane16_swap_b32_e32 v194, v196
	v_permlane16_swap_b32_e32 v195, v197
	global_store_dwordx4 v[70:71], v[190:193], off
	global_store_dwordx4 v[70:71], v[194:197], off offset:256
	global_load_dword v0, v[134:135], off offset:576
	v_add_co_u32_e32 v56, vcc, s3, v136
	v_lshl_add_u64 v[54:55], v[136:137], 0, s[0:1]
	s_nop 0
	v_addc_co_u32_e32 v57, vcc, 0, v137, vcc
	s_mov_b32 s3, 0xa0000
	s_mov_b64 s[0:1], 0xa0000
	s_waitcnt vmcnt(0)
; __device__ __forceinline__ unsigned cvt_pk_bf16(float lo, float hi) { unsigned r; asm volatile("v_cvt_pk_bf16_f32 %0, %1, %2" : "=v"(r) : "v"(lo), "v"(hi)); return r; }
; __device__ __forceinline__ float sigmoidf_(float x) { return __builtin_amdgcn_rcpf(1.f + __builtin_amdgcn_exp2f(-x * LOG2E)); }
;     __device__ __forceinline__ void operator()(const f32x4 (&acc)[2][2][4][2], const pg8::Unit& u, int wr, int wc, int fr, int fq) const {
;     ...
;         if (u.pn >= 12) {
;             const int col0 = (u.pn - 12) * 256 + wc * 32 + 4 * fq;
; #pragma unroll
;             for (int ai = 0; ai < 2; ++ai)
; #pragma unroll
;                 for (int m = 0; m < 4; ++m) { const int row = row0 + ai * 128 + m * 16; const float rs = __builtin_amdgcn_rsqf(ss[row] * (1.f / DM) + EPS);
; #pragma unroll
;                     for (int bj = 0; bj < 2; ++bj)
; #pragma unroll
;                         for (int n = 0; n < 2; ++n) { const f32x4 a = acc[ai][bj][m][n] * rs; u32x2 w; w.x = cvt_pk_bf16(sigmoidf_(a[0]), sigmoidf_(a[1])); w.y = cvt_pk_bf16(sigmoidf_(a[2]), sigmoidf_(a[3]));
;                             *(u32x2*)(G + (size_t)row * 2048 + col0 + bj * 128 + n * 16) = w; } }
;             return;
	v_fmamk_f32 v0, v0, 0x3a800000, v236
	v_rsq_f32_e32 v0, v0
	s_nop 0
	v_pk_mul_f32 v[52:53], v[52:53], v[0:1] op_sel_hi:[1,0]
	v_pk_mul_f32 v[50:51], v[50:51], v[0:1] op_sel_hi:[1,0]
	v_pk_mul_f32 v[38:39], v[38:39], v[0:1] op_sel_hi:[1,0]
	v_pk_mul_f32 v[48:49], v[48:49], v[0:1] op_sel_hi:[1,0]
	v_pk_mul_f32 v[46:47], v[46:47], v[0:1] op_sel_hi:[1,0]
	v_pk_mul_f32 v[44:45], v[44:45], v[0:1] op_sel_hi:[1,0]
	v_pk_mul_f32 v[42:43], v[42:43], v[0:1] op_sel_hi:[1,0]
	v_pk_mul_f32 v[40:41], v[40:41], v[0:1] op_sel_hi:[1,0]
	v_mul_f32_e32 v0, 0xbfb8aa3b, v50
	v_mul_f32_e32 v50, 0xbfb8aa3b, v51
	v_mul_f32_e32 v51, 0xbfb8aa3b, v52
	v_mul_f32_e32 v52, 0xbfb8aa3b, v53
	v_mul_f32_e32 v38, 0xbfb8aa3b, v38
	v_mul_f32_e32 v39, 0xbfb8aa3b, v39
	v_mul_f32_e32 v46, 0xbfb8aa3b, v46
	v_mul_f32_e32 v47, 0xbfb8aa3b, v47
	v_mul_f32_e32 v48, 0xbfb8aa3b, v48
	v_mul_f32_e32 v49, 0xbfb8aa3b, v49
	v_exp_f32_e32 v0, v0
	v_exp_f32_e32 v50, v50
	v_exp_f32_e32 v51, v51
	v_exp_f32_e32 v52, v52
	v_exp_f32_e32 v38, v38
	v_exp_f32_e32 v39, v39
	v_mul_f32_e32 v42, 0xbfb8aa3b, v42
	v_mul_f32_e32 v43, 0xbfb8aa3b, v43
	v_mul_f32_e32 v44, 0xbfb8aa3b, v44
	v_mul_f32_e32 v45, 0xbfb8aa3b, v45
	v_exp_f32_e32 v46, v46
	v_exp_f32_e32 v47, v47
	v_exp_f32_e32 v48, v48
	v_exp_f32_e32 v49, v49
	v_mul_f32_e32 v40, 0xbfb8aa3b, v40
	v_mul_f32_e32 v41, 0xbfb8aa3b, v41
	v_exp_f32_e32 v42, v42
	v_exp_f32_e32 v43, v43
	v_exp_f32_e32 v44, v44
	v_exp_f32_e32 v45, v45
	v_exp_f32_e32 v40, v40
	v_exp_f32_e32 v41, v41
	v_add_f32_e32 v0, 1.0, v0
	v_add_f32_e32 v50, 1.0, v50
	v_add_f32_e32 v51, 1.0, v51
	v_add_f32_e32 v52, 1.0, v52
	v_add_f32_e32 v38, 1.0, v38
	v_add_f32_e32 v39, 1.0, v39
	v_add_f32_e32 v46, 1.0, v46
	v_add_f32_e32 v47, 1.0, v47
	v_add_f32_e32 v48, 1.0, v48
	v_add_f32_e32 v49, 1.0, v49
	v_rcp_f32_e32 v0, v0
	v_rcp_f32_e32 v50, v50
	v_rcp_f32_e32 v51, v51
	v_rcp_f32_e32 v52, v52
	v_rcp_f32_e32 v53, v38
	v_rcp_f32_e32 v58, v39
	v_cvt_pk_bf16_f32 v190, v0, v50
	v_cvt_pk_bf16_f32 v191, v51, v52
	v_add_f32_e32 v42, 1.0, v42
	v_add_f32_e32 v43, 1.0, v43
	v_add_f32_e32 v44, 1.0, v44
	v_add_f32_e32 v45, 1.0, v45
	v_rcp_f32_e32 v46, v46
	v_rcp_f32_e32 v47, v47
	v_rcp_f32_e32 v48, v48
	v_rcp_f32_e32 v49, v49
	v_cvt_pk_bf16_f32 v192, v46, v47
	v_cvt_pk_bf16_f32 v193, v48, v49
	v_add_f32_e32 v40, 1.0, v40
	v_add_f32_e32 v41, 1.0, v41
	v_rcp_f32_e32 v42, v42
	v_rcp_f32_e32 v43, v43
	v_rcp_f32_e32 v44, v44
	v_rcp_f32_e32 v45, v45
	v_cvt_pk_bf16_f32 v194, v42, v43
	v_cvt_pk_bf16_f32 v195, v44, v45
	v_rcp_f32_e32 v40, v40
	v_rcp_f32_e32 v41, v41
	v_cvt_pk_bf16_f32 v196, v53, v58
	v_cvt_pk_bf16_f32 v197, v40, v41
	s_nop 1
	v_permlane16_swap_b32_e32 v190, v192
	v_permlane16_swap_b32_e32 v191, v193
	v_permlane16_swap_b32_e32 v194, v196
	v_permlane16_swap_b32_e32 v195, v197
	global_store_dwordx4 v[54:55], v[190:193], off
	global_store_dwordx4 v[54:55], v[194:197], off offset:256
	global_load_dword v0, v[134:135], off offset:640
	v_add_co_u32_e32 v40, vcc, s3, v136
	v_lshl_add_u64 v[38:39], v[136:137], 0, s[0:1]
	s_nop 0
	v_addc_co_u32_e32 v41, vcc, 0, v137, vcc
	s_mov_b32 s3, 0xb0000
	s_mov_b64 s[0:1], 0xb0000
	s_waitcnt vmcnt(0)
; __device__ __forceinline__ unsigned cvt_pk_bf16(float lo, float hi) { unsigned r; asm volatile("v_cvt_pk_bf16_f32 %0, %1, %2" : "=v"(r) : "v"(lo), "v"(hi)); return r; }
; __device__ __forceinline__ float sigmoidf_(float x) { return __builtin_amdgcn_rcpf(1.f + __builtin_amdgcn_exp2f(-x * LOG2E)); }
;     __device__ __forceinline__ void operator()(const f32x4 (&acc)[2][2][4][2], const pg8::Unit& u, int wr, int wc, int fr, int fq) const {
;     ...
;         if (u.pn >= 12) {
;             const int col0 = (u.pn - 12) * 256 + wc * 32 + 4 * fq;
; #pragma unroll
;             for (int ai = 0; ai < 2; ++ai)
; #pragma unroll
;                 for (int m = 0; m < 4; ++m) { const int row = row0 + ai * 128 + m * 16; const float rs = __builtin_amdgcn_rsqf(ss[row] * (1.f / DM) + EPS);
; #pragma unroll
;                     for (int bj = 0; bj < 2; ++bj)
; #pragma unroll
;                         for (int n = 0; n < 2; ++n) { const f32x4 a = acc[ai][bj][m][n] * rs; u32x2 w; w.x = cvt_pk_bf16(sigmoidf_(a[0]), sigmoidf_(a[1])); w.y = cvt_pk_bf16(sigmoidf_(a[2]), sigmoidf_(a[3]));
;                             *(u32x2*)(G + (size_t)row * 2048 + col0 + bj * 128 + n * 16) = w; } }
;             return;
	v_fmamk_f32 v0, v0, 0x3a800000, v236
	v_rsq_f32_e32 v0, v0
	s_nop 0
	v_pk_mul_f32 v[36:37], v[36:37], v[0:1] op_sel_hi:[1,0]
	v_pk_mul_f32 v[34:35], v[34:35], v[0:1] op_sel_hi:[1,0]
	v_pk_mul_f32 v[22:23], v[22:23], v[0:1] op_sel_hi:[1,0]
	v_pk_mul_f32 v[32:33], v[32:33], v[0:1] op_sel_hi:[1,0]
	v_pk_mul_f32 v[30:31], v[30:31], v[0:1] op_sel_hi:[1,0]
	v_pk_mul_f32 v[28:29], v[28:29], v[0:1] op_sel_hi:[1,0]
	v_pk_mul_f32 v[26:27], v[26:27], v[0:1] op_sel_hi:[1,0]
	v_pk_mul_f32 v[24:25], v[24:25], v[0:1] op_sel_hi:[1,0]
	v_mul_f32_e32 v0, 0xbfb8aa3b, v34
	v_mul_f32_e32 v34, 0xbfb8aa3b, v35
	v_mul_f32_e32 v35, 0xbfb8aa3b, v36
	v_mul_f32_e32 v36, 0xbfb8aa3b, v37
	v_mul_f32_e32 v22, 0xbfb8aa3b, v22
	v_mul_f32_e32 v23, 0xbfb8aa3b, v23
	v_mul_f32_e32 v30, 0xbfb8aa3b, v30
	v_mul_f32_e32 v31, 0xbfb8aa3b, v31
	v_mul_f32_e32 v32, 0xbfb8aa3b, v32
	v_mul_f32_e32 v33, 0xbfb8aa3b, v33
	v_exp_f32_e32 v0, v0
	v_exp_f32_e32 v34, v34
	v_exp_f32_e32 v35, v35
	v_exp_f32_e32 v36, v36
	v_exp_f32_e32 v22, v22
	v_exp_f32_e32 v23, v23
	v_mul_f32_e32 v26, 0xbfb8aa3b, v26
	v_mul_f32_e32 v27, 0xbfb8aa3b, v27
	v_mul_f32_e32 v28, 0xbfb8aa3b, v28
	v_mul_f32_e32 v29, 0xbfb8aa3b, v29
	v_exp_f32_e32 v30, v30
	v_exp_f32_e32 v31, v31
	v_exp_f32_e32 v32, v32
	v_exp_f32_e32 v33, v33
	v_mul_f32_e32 v24, 0xbfb8aa3b, v24
	v_mul_f32_e32 v25, 0xbfb8aa3b, v25
	v_exp_f32_e32 v26, v26
	v_exp_f32_e32 v27, v27
	v_exp_f32_e32 v28, v28
	v_exp_f32_e32 v29, v29
	v_exp_f32_e32 v24, v24
	v_exp_f32_e32 v25, v25
	v_add_f32_e32 v0, 1.0, v0
	v_add_f32_e32 v34, 1.0, v34
	v_add_f32_e32 v35, 1.0, v35
	v_add_f32_e32 v36, 1.0, v36
	v_add_f32_e32 v22, 1.0, v22
	v_add_f32_e32 v23, 1.0, v23
	v_add_f32_e32 v30, 1.0, v30
	v_add_f32_e32 v31, 1.0, v31
	v_add_f32_e32 v32, 1.0, v32
	v_add_f32_e32 v33, 1.0, v33
	v_rcp_f32_e32 v0, v0
	v_rcp_f32_e32 v34, v34
	v_rcp_f32_e32 v35, v35
	v_rcp_f32_e32 v36, v36
	v_rcp_f32_e32 v37, v22
	v_rcp_f32_e32 v42, v23
	v_cvt_pk_bf16_f32 v190, v0, v34
	v_cvt_pk_bf16_f32 v191, v35, v36
	v_add_f32_e32 v26, 1.0, v26
	v_add_f32_e32 v27, 1.0, v27
	v_add_f32_e32 v28, 1.0, v28
	v_add_f32_e32 v29, 1.0, v29
	v_rcp_f32_e32 v30, v30
	v_rcp_f32_e32 v31, v31
	v_rcp_f32_e32 v32, v32
	v_rcp_f32_e32 v33, v33
	v_cvt_pk_bf16_f32 v192, v30, v31
	v_cvt_pk_bf16_f32 v193, v32, v33
	v_add_f32_e32 v24, 1.0, v24
	v_add_f32_e32 v25, 1.0, v25
	v_rcp_f32_e32 v26, v26
	v_rcp_f32_e32 v27, v27
	v_rcp_f32_e32 v28, v28
	v_rcp_f32_e32 v29, v29
	v_cvt_pk_bf16_f32 v194, v26, v27
	v_cvt_pk_bf16_f32 v195, v28, v29
	v_rcp_f32_e32 v24, v24
	v_rcp_f32_e32 v25, v25
	v_cvt_pk_bf16_f32 v196, v37, v42
	v_cvt_pk_bf16_f32 v197, v24, v25
	s_nop 1
	v_permlane16_swap_b32_e32 v190, v192
	v_permlane16_swap_b32_e32 v191, v193
	v_permlane16_swap_b32_e32 v194, v196
	v_permlane16_swap_b32_e32 v195, v197
	global_store_dwordx4 v[38:39], v[190:193], off
	global_store_dwordx4 v[38:39], v[194:197], off offset:256
	global_load_dword v0, v[134:135], off offset:704
	v_add_co_u32_e32 v24, vcc, s3, v136
	v_lshl_add_u64 v[22:23], v[136:137], 0, s[0:1]
	s_nop 0
	v_addc_co_u32_e32 v25, vcc, 0, v137, vcc
	s_waitcnt vmcnt(0)
	v_fmamk_f32 v0, v0, 0x3a800000, v236
	v_rsq_f32_e32 v0, v0
	s_nop 0
	v_pk_mul_f32 v[20:21], v[20:21], v[0:1] op_sel_hi:[1,0]
	v_pk_mul_f32 v[18:19], v[18:19], v[0:1] op_sel_hi:[1,0]
	v_pk_mul_f32 v[6:7], v[6:7], v[0:1] op_sel_hi:[1,0]
	v_pk_mul_f32 v[16:17], v[16:17], v[0:1] op_sel_hi:[1,0]
	v_pk_mul_f32 v[14:15], v[14:15], v[0:1] op_sel_hi:[1,0]
	v_pk_mul_f32 v[12:13], v[12:13], v[0:1] op_sel_hi:[1,0]
	v_pk_mul_f32 v[10:11], v[10:11], v[0:1] op_sel_hi:[1,0]
	v_pk_mul_f32 v[8:9], v[8:9], v[0:1] op_sel_hi:[1,0]
	v_mul_f32_e32 v0, 0xbfb8aa3b, v18
	v_mul_f32_e32 v18, 0xbfb8aa3b, v19
	v_mul_f32_e32 v19, 0xbfb8aa3b, v20
	v_mul_f32_e32 v20, 0xbfb8aa3b, v21
	v_mul_f32_e32 v6, 0xbfb8aa3b, v6
	v_mul_f32_e32 v7, 0xbfb8aa3b, v7
	v_mul_f32_e32 v14, 0xbfb8aa3b, v14
	v_mul_f32_e32 v15, 0xbfb8aa3b, v15
	v_mul_f32_e32 v16, 0xbfb8aa3b, v16
	v_mul_f32_e32 v17, 0xbfb8aa3b, v17
	v_exp_f32_e32 v0, v0
	v_exp_f32_e32 v18, v18
	v_exp_f32_e32 v19, v19
	v_exp_f32_e32 v20, v20
	v_exp_f32_e32 v6, v6
	v_exp_f32_e32 v7, v7
	v_mul_f32_e32 v10, 0xbfb8aa3b, v10
	v_mul_f32_e32 v11, 0xbfb8aa3b, v11
	v_mul_f32_e32 v12, 0xbfb8aa3b, v12
	v_mul_f32_e32 v13, 0xbfb8aa3b, v13
	v_exp_f32_e32 v14, v14
	v_exp_f32_e32 v15, v15
	v_exp_f32_e32 v16, v16
	v_exp_f32_e32 v17, v17
	v_mul_f32_e32 v8, 0xbfb8aa3b, v8
	v_mul_f32_e32 v9, 0xbfb8aa3b, v9
	v_exp_f32_e32 v10, v10
	v_exp_f32_e32 v11, v11
	v_exp_f32_e32 v12, v12
	v_exp_f32_e32 v13, v13
	v_exp_f32_e32 v8, v8
	v_exp_f32_e32 v9, v9
	v_add_f32_e32 v0, 1.0, v0
	v_add_f32_e32 v18, 1.0, v18
	v_add_f32_e32 v19, 1.0, v19
	v_add_f32_e32 v20, 1.0, v20
	v_add_f32_e32 v6, 1.0, v6
	v_add_f32_e32 v7, 1.0, v7
	v_add_f32_e32 v14, 1.0, v14
	v_add_f32_e32 v15, 1.0, v15
	v_add_f32_e32 v16, 1.0, v16
	v_add_f32_e32 v17, 1.0, v17
	v_rcp_f32_e32 v0, v0
	v_rcp_f32_e32 v18, v18
	v_rcp_f32_e32 v19, v19
	v_rcp_f32_e32 v20, v20
	v_rcp_f32_e32 v21, v6
	v_rcp_f32_e32 v26, v7
	v_cvt_pk_bf16_f32 v190, v0, v18
	v_cvt_pk_bf16_f32 v191, v19, v20
	v_add_f32_e32 v10, 1.0, v10
	v_add_f32_e32 v11, 1.0, v11
	v_add_f32_e32 v12, 1.0, v12
	v_add_f32_e32 v13, 1.0, v13
	v_rcp_f32_e32 v14, v14
	v_rcp_f32_e32 v15, v15
	v_rcp_f32_e32 v16, v16
	v_rcp_f32_e32 v17, v17
	v_cvt_pk_bf16_f32 v192, v14, v15
	v_cvt_pk_bf16_f32 v193, v16, v17
	v_add_f32_e32 v8, 1.0, v8
	v_add_f32_e32 v9, 1.0, v9
	v_rcp_f32_e32 v10, v10
	v_rcp_f32_e32 v11, v11
	v_rcp_f32_e32 v12, v12
	v_rcp_f32_e32 v13, v13
	v_cvt_pk_bf16_f32 v194, v10, v11
	v_cvt_pk_bf16_f32 v195, v12, v13
	v_rcp_f32_e32 v8, v8
	v_rcp_f32_e32 v9, v9
	v_cvt_pk_bf16_f32 v196, v21, v26
	v_cvt_pk_bf16_f32 v197, v8, v9
	s_nop 1
	v_permlane16_swap_b32_e32 v190, v192
	v_permlane16_swap_b32_e32 v191, v193
	v_permlane16_swap_b32_e32 v194, v196
	v_permlane16_swap_b32_e32 v195, v197
	global_store_dwordx4 v[22:23], v[190:193], off
	global_store_dwordx4 v[22:23], v[194:197], off offset:256
	s_andn2_b64 vcc, exec, s[8:9]
	s_mov_b64 s[0:1], -1
	s_cbranch_vccz .LBB0_723

; __device__ __forceinline__ unsigned cvt_pk_bf16(float lo, float hi) { unsigned r; asm volatile("v_cvt_pk_bf16_f32 %0, %1, %2" : "=v"(r) : "v"(lo), "v"(hi)); return r; }
;     __device__ __forceinline__ void operator()(const f32x4 (&acc)[2][2][4][2], const pg8::Unit& u, int wr, int wc, int fr, int fq) const {
;     ...
;             for (int m = 0; m < 4; ++m) { const int row = row0 + ai * 128 + m * 16; const float rs = __builtin_amdgcn_rsqf(ss[row] * (1.f / DM) + EPS);
;                 f32x4 v[2][2]; float s = 0.f;
; #pragma unroll
;                 for (int bj = 0; bj < 2; ++bj)
; #pragma unroll
;                     for (int n = 0; n < 2; ++n) { v[bj][n] = acc[ai][bj][m][n] * rs; s += (v[bj][n][0] * v[bj][n][0] + v[bj][n][1] * v[bj][n][1]) + (v[bj][n][2] * v[bj][n][2] + v[bj][n][3] * v[bj][n][3]); }
;                 s += __shfl_xor(s, 16); s += __shfl_xor(s, 32);
;                 const float inv = (kind < 2) ? __builtin_amdgcn_rsqf(s * (1.f / 64.f) + EPS) : 1.f;
; #pragma unroll
;                 for (int bj = 0; bj < 2; ++bj)
; #pragma unroll
;                     for (int n = 0; n < 2; ++n) v[bj][n] = v[bj][n] * gv[bj][n] * inv;
;                 if (row < MPR) {
;                     const int b = row >> 11, sq = row & 2047, p = ((sq & (dil - 1)) << (11 - sh)) + (sq >> sh);
;                     bf16* dst = (bf16*)(wsb + boff) + ((size_t)(b * nh + idx) * 2048 + p) * 64;
; #pragma unroll
;                     for (int bj = 0; bj < 2; ++bj)
; #pragma unroll
;                         for (int n = 0; n < 2; ++n) { u32x2 w; w.x = cvt_pk_bf16(v[bj][n][0], v[bj][n][1]); w.y = cvt_pk_bf16(v[bj][n][2], v[bj][n][3]); *(u32x2*)(dst + 32 * bj + 16 * n + 4 * fq) = w; }
;                     if (kind > 0 && sq >= 2048 - win) {
.LBB0_617:
	s_or_saveexec_b64 s[62:63], s[0:1]
	s_waitcnt lgkmcnt(0)
	v_add_f32_e32 v167, v167, v172
	v_fmamk_f32 v167, v167, 0x3c800000, v236
	v_rsq_f32_e32 v167, v167
	s_ashr_i32 s4, s24, 11
	v_pk_mul_f32 v[150:151], v[148:149], v[150:151]
	v_pk_mul_f32 v[174:175], v[146:147], v[152:153]
	v_cndmask_b32_e64 v172, 1.0, v167, s[10:11]
	s_mul_i32 s0, s96, s4
	v_pk_mul_f32 v[152:153], v[150:151], v[172:173] op_sel_hi:[1,0]
	v_pk_mul_f32 v[150:151], v[174:175], v[172:173] op_sel_hi:[1,0]
	v_pk_mul_f32 v[154:155], v[144:145], v[154:155]
	v_pk_mul_f32 v[174:175], v[142:143], v[156:157]
	s_add_i32 s0, s56, s0
	v_pk_mul_f32 v[156:157], v[154:155], v[172:173] op_sel_hi:[1,0]
	v_pk_mul_f32 v[154:155], v[174:175], v[172:173] op_sel_hi:[1,0]
	v_pk_mul_f32 v[158:159], v[140:141], v[158:159]
	v_pk_mul_f32 v[174:175], v[138:139], v[160:161]
	s_ashr_i32 s1, s0, 31
	v_pk_mul_f32 v[160:161], v[158:159], v[172:173] op_sel_hi:[1,0]
	v_pk_mul_f32 v[158:159], v[174:175], v[172:173] op_sel_hi:[1,0]
	v_pk_mul_f32 v[162:163], v[136:137], v[162:163]
	v_pk_mul_f32 v[174:175], v[134:135], v[164:165]
	s_sub_i32 s78, 11, s41
	s_sub_i32 s33, 0x800, s70
	v_mov_b32_e32 v0, v168
	s_lshl_b64 s[0:1], s[0:1], 18
	s_mul_hi_i32 s5, s70, s4
	s_mul_i32 s4, s70, s4
	v_pk_mul_f32 v[164:165], v[162:163], v[172:173] op_sel_hi:[1,0]
	v_pk_mul_f32 v[162:163], v[174:175], v[172:173] op_sel_hi:[1,0]
	v_mov_b64_e32 v[178:179], s[64:65]
	v_and_b32_e32 v174, 4, v204
	v_mul_u32_u24_e32 v174, 6, v174
	v_lshl_add_u32 v174, v204, 1, v174
	s_xor_b64 exec, exec, s[62:63]
	s_cbranch_execz .LBB0_621
	s_add_u32 s25, s14, s43
	s_addc_u32 s64, s15, 0
	s_add_u32 s25, s25, s51
	v_and_b32_e32 v167, 0x7cf, v166
	v_lshlrev_b32_e32 v172, s78, v166
	s_addc_u32 s65, s64, 0
	v_and_b32_e32 v172, 0x7fe, v172
	v_lshrrev_b32_e32 v173, s41, v167
	s_add_u32 s64, s25, s0
	s_addc_u32 s65, s65, s1
	v_add_lshl_u32 v172, v172, v173, 7
	v_mov_b32_e32 v173, v1
	v_lshl_add_u64 v[172:173], s[64:65], 0, v[172:173]
	v_mov_b32_e32 v175, v1
	v_lshl_add_u64 v[172:173], v[172:173], 0, v[174:175]
	v_cvt_pk_bf16_f32 v190, v150, v151
	v_cvt_pk_bf16_f32 v191, v152, v153
	v_cvt_pk_bf16_f32 v192, v154, v155
	v_cvt_pk_bf16_f32 v193, v156, v157
	v_cvt_pk_bf16_f32 v194, v158, v159
	v_cvt_pk_bf16_f32 v195, v160, v161
	v_cmp_le_i32_e32 vcc, s33, v167
	v_cvt_pk_bf16_f32 v196, v162, v163
	v_cvt_pk_bf16_f32 v197, v164, v165
	s_and_b64 vcc, s[54:55], vcc
	s_mov_b64 s[68:69], s[6:7]
	s_nop 1
	v_permlane16_swap_b32_e32 v190, v192
	v_permlane16_swap_b32_e32 v191, v193
	v_permlane16_swap_b32_e32 v194, v196
	v_permlane16_swap_b32_e32 v195, v197
	global_store_dwordx4 v[172:173], v[190:193], off
	global_store_dwordx4 v[172:173], v[194:197], off offset:64
	s_and_saveexec_b64 s[66:67], vcc
	s_cbranch_execz .LBB0_620
	v_subrev_u32_e32 v172, s33, v167
	v_mov_b32_e32 v173, v1
	v_lshl_add_u64 v[172:173], s[4:5], 0, v[172:173]
	s_lshl_b64 s[64:65], s[52:53], 2
	v_lshl_add_u64 v[172:173], v[172:173], 1, v[0:1]
	s_add_u32 s64, s12, s64
	v_lshlrev_b64 v[172:173], s50, v[172:173]
	s_addc_u32 s65, s13, s65
	v_lshl_add_u64 v[176:177], v[172:173], 0, s[18:19]
	s_or_b64 s[68:69], s[6:7], exec

; __device__ __forceinline__ unsigned cvt_pk_bf16(float lo, float hi) { unsigned r; asm volatile("v_cvt_pk_bf16_f32 %0, %1, %2" : "=v"(r) : "v"(lo), "v"(hi)); return r; }
;     __device__ __forceinline__ void operator()(const f32x4 (&acc)[2][2][4][2], const pg8::Unit& u, int wr, int wc, int fr, int fq) const {
;     ...
;             for (int m = 0; m < 4; ++m) { const int row = row0 + ai * 128 + m * 16; const float rs = __builtin_amdgcn_rsqf(ss[row] * (1.f / DM) + EPS);
;                 f32x4 v[2][2]; float s = 0.f;
; #pragma unroll
;                 for (int bj = 0; bj < 2; ++bj)
; #pragma unroll
;                     for (int n = 0; n < 2; ++n) { v[bj][n] = acc[ai][bj][m][n] * rs; s += (v[bj][n][0] * v[bj][n][0] + v[bj][n][1] * v[bj][n][1]) + (v[bj][n][2] * v[bj][n][2] + v[bj][n][3] * v[bj][n][3]); }
;                 s += __shfl_xor(s, 16); s += __shfl_xor(s, 32);
;                 const float inv = (kind < 2) ? __builtin_amdgcn_rsqf(s * (1.f / 64.f) + EPS) : 1.f;
; #pragma unroll
;                 for (int bj = 0; bj < 2; ++bj)
; #pragma unroll
;                     for (int n = 0; n < 2; ++n) v[bj][n] = v[bj][n] * gv[bj][n] * inv;
;                 if (row < MPR) {
;                     const int b = row >> 11, sq = row & 2047, p = ((sq & (dil - 1)) << (11 - sh)) + (sq >> sh);
;                     bf16* dst = (bf16*)(wsb + boff) + ((size_t)(b * nh + idx) * 2048 + p) * 64;
; #pragma unroll
;                     for (int bj = 0; bj < 2; ++bj)
; #pragma unroll
;                         for (int n = 0; n < 2; ++n) { u32x2 w; w.x = cvt_pk_bf16(v[bj][n][0], v[bj][n][1]); w.y = cvt_pk_bf16(v[bj][n][2], v[bj][n][3]); *(u32x2*)(dst + 32 * bj + 16 * n + 4 * fq) = w; }
;                     if (kind > 0 && sq >= 2048 - win) {
.LBB0_631:
	s_or_saveexec_b64 s[62:63], s[62:63]
	s_waitcnt lgkmcnt(0)
	v_add_f32_e32 v167, v167, v173
	v_fmamk_f32 v167, v167, 0x3c800000, v236
	v_rsq_f32_e32 v167, v167
	v_pk_mul_f32 v[182:183], v[138:139], v[160:161]
	v_pk_mul_f32 v[158:159], v[140:141], v[158:159]
	v_pk_mul_f32 v[150:151], v[146:147], v[150:151]
	v_cndmask_b32_e64 v180, 1.0, v167, s[10:11]
	v_pk_mul_f32 v[152:153], v[148:149], v[152:153]
	v_pk_mul_f32 v[154:155], v[142:143], v[154:155]
	v_pk_mul_f32 v[156:157], v[144:145], v[156:157]
	v_pk_mul_f32 v[160:161], v[158:159], v[180:181] op_sel_hi:[1,0]
	v_pk_mul_f32 v[158:159], v[182:183], v[180:181] op_sel_hi:[1,0]
	v_pk_mul_f32 v[182:183], v[134:135], v[164:165]
	v_pk_mul_f32 v[162:163], v[136:137], v[162:163]
	v_pk_mul_f32 v[152:153], v[152:153], v[180:181] op_sel_hi:[1,0]
	v_pk_mul_f32 v[150:151], v[150:151], v[180:181] op_sel_hi:[1,0]
	v_pk_mul_f32 v[156:157], v[156:157], v[180:181] op_sel_hi:[1,0]
	v_pk_mul_f32 v[154:155], v[154:155], v[180:181] op_sel_hi:[1,0]
	v_pk_mul_f32 v[164:165], v[162:163], v[180:181] op_sel_hi:[1,0]
	v_pk_mul_f32 v[162:163], v[182:183], v[180:181] op_sel_hi:[1,0]
	v_mov_b64_e32 v[180:181], s[64:65]
	s_xor_b64 exec, exec, s[62:63]
	s_cbranch_execz .LBB0_635
	s_add_u32 s25, s14, s43
	s_addc_u32 s64, s15, 0
	s_add_u32 s25, s25, s51
	v_and_b32_e32 v167, 0x7df, v176
	v_lshlrev_b32_e32 v173, s78, v176
	s_addc_u32 s65, s64, 0
	v_and_b32_e32 v173, 0x7fe, v173
	v_lshrrev_b32_e32 v175, s41, v167
	s_add_u32 s64, s25, s0
	s_addc_u32 s65, s65, s1
	v_add_lshl_u32 v176, v173, v175, 7
	v_mov_b32_e32 v177, v1
	v_lshl_add_u64 v[176:177], s[64:65], 0, v[176:177]
	v_mov_b32_e32 v175, v1
	v_lshl_add_u64 v[176:177], v[176:177], 0, v[174:175]
	v_cvt_pk_bf16_f32 v190, v150, v151
	v_cvt_pk_bf16_f32 v191, v152, v153
	v_cvt_pk_bf16_f32 v192, v154, v155
	v_cvt_pk_bf16_f32 v193, v156, v157
	v_cvt_pk_bf16_f32 v194, v158, v159
	v_cvt_pk_bf16_f32 v195, v160, v161
	v_cmp_le_i32_e32 vcc, s33, v167
	v_cvt_pk_bf16_f32 v196, v162, v163
	v_cvt_pk_bf16_f32 v197, v164, v165
	s_and_b64 vcc, s[54:55], vcc
	s_mov_b64 s[68:69], s[6:7]
	s_nop 1
	v_permlane16_swap_b32_e32 v190, v192
	v_permlane16_swap_b32_e32 v191, v193
	v_permlane16_swap_b32_e32 v194, v196
	v_permlane16_swap_b32_e32 v195, v197
	global_store_dwordx4 v[176:177], v[190:193], off
	global_store_dwordx4 v[176:177], v[194:197], off offset:64
	s_and_saveexec_b64 s[66:67], vcc
	s_cbranch_execz .LBB0_634
	v_subrev_u32_e32 v176, s33, v167
	v_mov_b32_e32 v177, v1
	v_lshl_add_u64 v[176:177], s[4:5], 0, v[176:177]
	s_lshl_b64 s[64:65], s[52:53], 2
	v_lshl_add_u64 v[176:177], v[176:177], 1, v[0:1]
	s_add_u32 s64, s12, s64
	v_lshlrev_b64 v[176:177], s50, v[176:177]
	s_addc_u32 s65, s13, s65
	v_lshl_add_u64 v[178:179], v[176:177], 0, s[18:19]
	s_or_b64 s[68:69], s[6:7], exec

; __device__ __forceinline__ unsigned cvt_pk_bf16(float lo, float hi) { unsigned r; asm volatile("v_cvt_pk_bf16_f32 %0, %1, %2" : "=v"(r) : "v"(lo), "v"(hi)); return r; }
;     __device__ __forceinline__ void operator()(const f32x4 (&acc)[2][2][4][2], const pg8::Unit& u, int wr, int wc, int fr, int fq) const {
;     ...
;             for (int m = 0; m < 4; ++m) { const int row = row0 + ai * 128 + m * 16; const float rs = __builtin_amdgcn_rsqf(ss[row] * (1.f / DM) + EPS);
;                 f32x4 v[2][2]; float s = 0.f;
; #pragma unroll
;                 for (int bj = 0; bj < 2; ++bj)
; #pragma unroll
;                     for (int n = 0; n < 2; ++n) { v[bj][n] = acc[ai][bj][m][n] * rs; s += (v[bj][n][0] * v[bj][n][0] + v[bj][n][1] * v[bj][n][1]) + (v[bj][n][2] * v[bj][n][2] + v[bj][n][3] * v[bj][n][3]); }
;                 s += __shfl_xor(s, 16); s += __shfl_xor(s, 32);
;                 const float inv = (kind < 2) ? __builtin_amdgcn_rsqf(s * (1.f / 64.f) + EPS) : 1.f;
; #pragma unroll
;                 for (int bj = 0; bj < 2; ++bj)
; #pragma unroll
;                     for (int n = 0; n < 2; ++n) v[bj][n] = v[bj][n] * gv[bj][n] * inv;
;                 if (row < MPR) {
;                     const int b = row >> 11, sq = row & 2047, p = ((sq & (dil - 1)) << (11 - sh)) + (sq >> sh);
;                     bf16* dst = (bf16*)(wsb + boff) + ((size_t)(b * nh + idx) * 2048 + p) * 64;
; #pragma unroll
;                     for (int bj = 0; bj < 2; ++bj)
; #pragma unroll
;                         for (int n = 0; n < 2; ++n) { u32x2 w; w.x = cvt_pk_bf16(v[bj][n][0], v[bj][n][1]); w.y = cvt_pk_bf16(v[bj][n][2], v[bj][n][3]); *(u32x2*)(dst + 32 * bj + 16 * n + 4 * fq) = w; }
;                     if (kind > 0 && sq >= 2048 - win) {
.LBB0_645:
	s_or_saveexec_b64 s[62:63], s[62:63]
	s_waitcnt lgkmcnt(0)
	v_add_f32_e32 v167, v167, v173
	v_fmamk_f32 v167, v167, 0x3c800000, v236
	v_rsq_f32_e32 v167, v167
	v_pk_mul_f32 v[182:183], v[138:139], v[160:161]
	v_pk_mul_f32 v[158:159], v[140:141], v[158:159]
	v_pk_mul_f32 v[150:151], v[146:147], v[150:151]
	v_cndmask_b32_e64 v180, 1.0, v167, s[10:11]
	v_pk_mul_f32 v[152:153], v[148:149], v[152:153]
	v_pk_mul_f32 v[154:155], v[142:143], v[154:155]
	v_pk_mul_f32 v[156:157], v[144:145], v[156:157]
	v_pk_mul_f32 v[160:161], v[158:159], v[180:181] op_sel_hi:[1,0]
	v_pk_mul_f32 v[158:159], v[182:183], v[180:181] op_sel_hi:[1,0]
	v_pk_mul_f32 v[182:183], v[134:135], v[164:165]
	v_pk_mul_f32 v[162:163], v[136:137], v[162:163]
	v_pk_mul_f32 v[152:153], v[152:153], v[180:181] op_sel_hi:[1,0]
	v_pk_mul_f32 v[150:151], v[150:151], v[180:181] op_sel_hi:[1,0]
	v_pk_mul_f32 v[156:157], v[156:157], v[180:181] op_sel_hi:[1,0]
	v_pk_mul_f32 v[154:155], v[154:155], v[180:181] op_sel_hi:[1,0]
	v_pk_mul_f32 v[164:165], v[162:163], v[180:181] op_sel_hi:[1,0]
	v_pk_mul_f32 v[162:163], v[182:183], v[180:181] op_sel_hi:[1,0]
	v_mov_b64_e32 v[180:181], s[64:65]
	s_xor_b64 exec, exec, s[62:63]
	s_cbranch_execz .LBB0_649
	s_add_u32 s25, s14, s43
	s_addc_u32 s64, s15, 0
	s_add_u32 s25, s25, s51
	v_and_b32_e32 v167, 0x7ef, v176
	v_lshlrev_b32_e32 v173, s78, v176
	s_addc_u32 s65, s64, 0
	v_and_b32_e32 v173, 0x7fe, v173
	v_lshrrev_b32_e32 v175, s41, v167
	s_add_u32 s64, s25, s0
	s_addc_u32 s65, s65, s1
	v_add_lshl_u32 v176, v173, v175, 7
	v_mov_b32_e32 v177, v1
	v_lshl_add_u64 v[176:177], s[64:65], 0, v[176:177]
	v_mov_b32_e32 v175, v1
	v_lshl_add_u64 v[176:177], v[176:177], 0, v[174:175]
	v_cvt_pk_bf16_f32 v190, v150, v151
	v_cvt_pk_bf16_f32 v191, v152, v153
	v_cvt_pk_bf16_f32 v192, v154, v155
	v_cvt_pk_bf16_f32 v193, v156, v157
	v_cvt_pk_bf16_f32 v194, v158, v159
	v_cvt_pk_bf16_f32 v195, v160, v161
	v_cmp_le_i32_e32 vcc, s33, v167
	v_cvt_pk_bf16_f32 v196, v162, v163
	v_cvt_pk_bf16_f32 v197, v164, v165
	s_and_b64 vcc, s[54:55], vcc
	s_mov_b64 s[68:69], s[6:7]
	s_nop 1
	v_permlane16_swap_b32_e32 v190, v192
	v_permlane16_swap_b32_e32 v191, v193
	v_permlane16_swap_b32_e32 v194, v196
	v_permlane16_swap_b32_e32 v195, v197
	global_store_dwordx4 v[176:177], v[190:193], off
	global_store_dwordx4 v[176:177], v[194:197], off offset:64
	s_and_saveexec_b64 s[66:67], vcc
	s_cbranch_execz .LBB0_648
	v_subrev_u32_e32 v176, s33, v167
	v_mov_b32_e32 v177, v1
	v_lshl_add_u64 v[176:177], s[4:5], 0, v[176:177]
	s_lshl_b64 s[64:65], s[52:53], 2
	v_lshl_add_u64 v[176:177], v[176:177], 1, v[0:1]
	s_add_u32 s64, s12, s64
	v_lshlrev_b64 v[176:177], s50, v[176:177]
	s_addc_u32 s65, s13, s65
	v_lshl_add_u64 v[178:179], v[176:177], 0, s[18:19]
	s_or_b64 s[68:69], s[6:7], exec

; __device__ __forceinline__ unsigned cvt_pk_bf16(float lo, float hi) { unsigned r; asm volatile("v_cvt_pk_bf16_f32 %0, %1, %2" : "=v"(r) : "v"(lo), "v"(hi)); return r; }
;     __device__ __forceinline__ void operator()(const f32x4 (&acc)[2][2][4][2], const pg8::Unit& u, int wr, int wc, int fr, int fq) const {
;     ...
;             for (int m = 0; m < 4; ++m) { const int row = row0 + ai * 128 + m * 16; const float rs = __builtin_amdgcn_rsqf(ss[row] * (1.f / DM) + EPS);
;                 f32x4 v[2][2]; float s = 0.f;
; #pragma unroll
;                 for (int bj = 0; bj < 2; ++bj)
; #pragma unroll
;                     for (int n = 0; n < 2; ++n) { v[bj][n] = acc[ai][bj][m][n] * rs; s += (v[bj][n][0] * v[bj][n][0] + v[bj][n][1] * v[bj][n][1]) + (v[bj][n][2] * v[bj][n][2] + v[bj][n][3] * v[bj][n][3]); }
;                 s += __shfl_xor(s, 16); s += __shfl_xor(s, 32);
;                 const float inv = (kind < 2) ? __builtin_amdgcn_rsqf(s * (1.f / 64.f) + EPS) : 1.f;
; #pragma unroll
;                 for (int bj = 0; bj < 2; ++bj)
; #pragma unroll
;                     for (int n = 0; n < 2; ++n) v[bj][n] = v[bj][n] * gv[bj][n] * inv;
;                 if (row < MPR) {
;                     const int b = row >> 11, sq = row & 2047, p = ((sq & (dil - 1)) << (11 - sh)) + (sq >> sh);
;                     bf16* dst = (bf16*)(wsb + boff) + ((size_t)(b * nh + idx) * 2048 + p) * 64;
; #pragma unroll
;                     for (int bj = 0; bj < 2; ++bj)
; #pragma unroll
;                         for (int n = 0; n < 2; ++n) { u32x2 w; w.x = cvt_pk_bf16(v[bj][n][0], v[bj][n][1]); w.y = cvt_pk_bf16(v[bj][n][2], v[bj][n][3]); *(u32x2*)(dst + 32 * bj + 16 * n + 4 * fq) = w; }
;                     if (kind > 0 && sq >= 2048 - win) {
.LBB0_659:
	s_or_saveexec_b64 s[62:63], s[62:63]
	s_waitcnt lgkmcnt(0)
	v_add_f32_e32 v167, v167, v173
	v_fmamk_f32 v167, v167, 0x3c800000, v236
	v_rsq_f32_e32 v167, v167
	v_pk_mul_f32 v[182:183], v[138:139], v[160:161]
	v_pk_mul_f32 v[158:159], v[140:141], v[158:159]
	v_pk_mul_f32 v[150:151], v[146:147], v[150:151]
	v_cndmask_b32_e64 v180, 1.0, v167, s[10:11]
	v_pk_mul_f32 v[152:153], v[148:149], v[152:153]
	v_pk_mul_f32 v[154:155], v[142:143], v[154:155]
	v_pk_mul_f32 v[156:157], v[144:145], v[156:157]
	v_pk_mul_f32 v[160:161], v[158:159], v[180:181] op_sel_hi:[1,0]
	v_pk_mul_f32 v[158:159], v[182:183], v[180:181] op_sel_hi:[1,0]
	v_pk_mul_f32 v[182:183], v[134:135], v[164:165]
	v_pk_mul_f32 v[162:163], v[136:137], v[162:163]
	v_pk_mul_f32 v[152:153], v[152:153], v[180:181] op_sel_hi:[1,0]
	v_pk_mul_f32 v[150:151], v[150:151], v[180:181] op_sel_hi:[1,0]
	v_pk_mul_f32 v[156:157], v[156:157], v[180:181] op_sel_hi:[1,0]
	v_pk_mul_f32 v[154:155], v[154:155], v[180:181] op_sel_hi:[1,0]
	v_pk_mul_f32 v[164:165], v[162:163], v[180:181] op_sel_hi:[1,0]
	v_pk_mul_f32 v[162:163], v[182:183], v[180:181] op_sel_hi:[1,0]
	v_mov_b64_e32 v[180:181], s[64:65]
	s_xor_b64 exec, exec, s[62:63]
	s_cbranch_execz .LBB0_663
	s_add_u32 s24, s14, s43
	s_addc_u32 s25, s15, 0
	s_add_u32 s24, s24, s51
	v_and_b32_e32 v167, 0x7ff, v176
	v_lshlrev_b32_e32 v173, s78, v176
	s_addc_u32 s25, s25, 0
	v_and_b32_e32 v173, 0x7fe, v173
	v_lshrrev_b32_e32 v175, s41, v167
	s_add_u32 s0, s24, s0
	s_addc_u32 s1, s25, s1
	v_add_lshl_u32 v176, v173, v175, 7
	v_mov_b32_e32 v177, v1
	v_lshl_add_u64 v[176:177], s[0:1], 0, v[176:177]
	v_mov_b32_e32 v175, v1
	v_lshl_add_u64 v[176:177], v[176:177], 0, v[174:175]
	v_cvt_pk_bf16_f32 v190, v150, v151
	v_cvt_pk_bf16_f32 v191, v152, v153
	v_cvt_pk_bf16_f32 v192, v154, v155
	v_cvt_pk_bf16_f32 v193, v156, v157
	v_cvt_pk_bf16_f32 v194, v158, v159
	v_cvt_pk_bf16_f32 v195, v160, v161
	v_cmp_le_i32_e32 vcc, s33, v167
	v_cvt_pk_bf16_f32 v196, v162, v163
	v_cvt_pk_bf16_f32 v197, v164, v165
	s_and_b64 s[24:25], s[54:55], vcc
	s_mov_b64 s[66:67], s[6:7]
	s_nop 1
	v_permlane16_swap_b32_e32 v190, v192
	v_permlane16_swap_b32_e32 v191, v193
	v_permlane16_swap_b32_e32 v194, v196
	v_permlane16_swap_b32_e32 v195, v197
	global_store_dwordx4 v[176:177], v[190:193], off
	global_store_dwordx4 v[176:177], v[194:197], off offset:64
	s_and_saveexec_b64 s[64:65], s[24:25]
	s_cbranch_execz .LBB0_662
	v_subrev_u32_e32 v176, s33, v167
	v_mov_b32_e32 v177, v1
	v_lshl_add_u64 v[176:177], s[4:5], 0, v[176:177]
	s_lshl_b64 s[0:1], s[52:53], 2
	v_lshl_add_u64 v[176:177], v[176:177], 1, v[0:1]
	s_add_u32 s0, s12, s0
	v_lshlrev_b64 v[176:177], s50, v[176:177]
	s_addc_u32 s1, s13, s1
	v_lshl_add_u64 v[178:179], v[176:177], 0, s[18:19]
	s_or_b64 s[66:67], s[6:7], exec

; __device__ __forceinline__ unsigned cvt_pk_bf16(float lo, float hi) { unsigned r; asm volatile("v_cvt_pk_bf16_f32 %0, %1, %2" : "=v"(r) : "v"(lo), "v"(hi)); return r; }
;     __device__ __forceinline__ void operator()(const f32x4 (&acc)[2][2][4][2], const pg8::Unit& u, int wr, int wc, int fr, int fq) const {
;     ...
;             for (int m = 0; m < 4; ++m) { const int row = row0 + ai * 128 + m * 16; const float rs = __builtin_amdgcn_rsqf(ss[row] * (1.f / DM) + EPS);
;                 f32x4 v[2][2]; float s = 0.f;
; #pragma unroll
;                 for (int bj = 0; bj < 2; ++bj)
; #pragma unroll
;                     for (int n = 0; n < 2; ++n) { v[bj][n] = acc[ai][bj][m][n] * rs; s += (v[bj][n][0] * v[bj][n][0] + v[bj][n][1] * v[bj][n][1]) + (v[bj][n][2] * v[bj][n][2] + v[bj][n][3] * v[bj][n][3]); }
;                 s += __shfl_xor(s, 16); s += __shfl_xor(s, 32);
;                 const float inv = (kind < 2) ? __builtin_amdgcn_rsqf(s * (1.f / 64.f) + EPS) : 1.f;
; #pragma unroll
;                 for (int bj = 0; bj < 2; ++bj)
; #pragma unroll
;                     for (int n = 0; n < 2; ++n) v[bj][n] = v[bj][n] * gv[bj][n] * inv;
;                 if (row < MPR) {
;                     const int b = row >> 11, sq = row & 2047, p = ((sq & (dil - 1)) << (11 - sh)) + (sq >> sh);
;                     bf16* dst = (bf16*)(wsb + boff) + ((size_t)(b * nh + idx) * 2048 + p) * 64;
; #pragma unroll
;                     for (int bj = 0; bj < 2; ++bj)
; #pragma unroll
;                         for (int n = 0; n < 2; ++n) { u32x2 w; w.x = cvt_pk_bf16(v[bj][n][0], v[bj][n][1]); w.y = cvt_pk_bf16(v[bj][n][2], v[bj][n][3]); *(u32x2*)(dst + 32 * bj + 16 * n + 4 * fq) = w; }
;                     if (kind > 0 && sq >= 2048 - win) {
.LBB0_673:
	s_or_saveexec_b64 s[4:5], s[4:5]
	s_waitcnt lgkmcnt(0)
	v_add_f32_e32 v173, v173, v175
	v_fmamk_f32 v173, v173, 0x3c800000, v236
	v_rsq_f32_e32 v173, v173
	v_ashrrev_i32_e32 v182, 11, v167
	v_mov_b32_e32 v176, s56
	v_mad_i32_i24 v176, s96, v182, v176
	v_ashrrev_i32_e32 v177, 31, v176
	v_lshlrev_b64 v[178:179], 18, v[176:177]
	v_mad_i64_i32 v[176:177], s[24:25], s70, v182, 0
	v_cndmask_b32_e64 v182, 1.0, v173, s[10:11]
	v_pk_mul_f32 v[186:187], v[138:139], v[160:161]
	v_pk_mul_f32 v[158:159], v[140:141], v[158:159]
	v_pk_mul_f32 v[150:151], v[146:147], v[150:151]
	v_pk_mul_f32 v[152:153], v[148:149], v[152:153]
	v_pk_mul_f32 v[154:155], v[142:143], v[154:155]
	v_pk_mul_f32 v[156:157], v[144:145], v[156:157]
	v_pk_mul_f32 v[160:161], v[158:159], v[182:183] op_sel_hi:[1,0]
	v_pk_mul_f32 v[158:159], v[186:187], v[182:183] op_sel_hi:[1,0]
	v_pk_mul_f32 v[186:187], v[134:135], v[164:165]
	v_pk_mul_f32 v[162:163], v[136:137], v[162:163]
	v_pk_mul_f32 v[152:153], v[152:153], v[182:183] op_sel_hi:[1,0]
	v_pk_mul_f32 v[150:151], v[150:151], v[182:183] op_sel_hi:[1,0]
	v_pk_mul_f32 v[156:157], v[156:157], v[182:183] op_sel_hi:[1,0]
	v_pk_mul_f32 v[154:155], v[154:155], v[182:183] op_sel_hi:[1,0]
	v_pk_mul_f32 v[164:165], v[162:163], v[182:183] op_sel_hi:[1,0]
	v_pk_mul_f32 v[162:163], v[186:187], v[182:183] op_sel_hi:[1,0]
	v_mov_b64_e32 v[182:183], s[6:7]
	s_xor_b64 exec, exec, s[4:5]
	s_cbranch_execz .LBB0_677
	s_add_u32 s6, s14, s43
	s_addc_u32 s7, s15, 0
	v_and_b32_e32 v173, 0x7cf, v167
	v_lshlrev_b32_e32 v167, s78, v167
	s_add_u32 s6, s6, s51
	v_and_b32_e32 v167, 0x7fe, v167
	v_lshrrev_b32_e32 v175, s41, v173
	s_addc_u32 s7, s7, 0
	v_lshl_add_u64 v[180:181], s[6:7], 0, v[178:179]
	v_add_lshl_u32 v182, v167, v175, 7
	v_mov_b32_e32 v183, v1
	v_lshl_add_u64 v[180:181], v[180:181], 0, v[182:183]
	v_mov_b32_e32 v175, v1
	v_lshl_add_u64 v[180:181], v[180:181], 0, v[174:175]
	v_cvt_pk_bf16_f32 v190, v150, v151
	v_cvt_pk_bf16_f32 v191, v152, v153
	v_cvt_pk_bf16_f32 v192, v154, v155
	v_cvt_pk_bf16_f32 v193, v156, v157
	v_cmp_le_i32_e32 vcc, s33, v173
	v_cvt_pk_bf16_f32 v194, v158, v159
	v_cvt_pk_bf16_f32 v195, v160, v161
	s_and_b64 s[24:25], s[54:55], vcc
	s_mov_b64 s[64:65], s[0:1]
	v_cvt_pk_bf16_f32 v196, v162, v163
	v_cvt_pk_bf16_f32 v197, v164, v165
	s_nop 1
	v_permlane16_swap_b32_e32 v190, v192
	v_permlane16_swap_b32_e32 v191, v193
	v_permlane16_swap_b32_e32 v194, v196
	v_permlane16_swap_b32_e32 v195, v197
	global_store_dwordx4 v[180:181], v[190:193], off
	global_store_dwordx4 v[180:181], v[194:197], off offset:64
	s_and_saveexec_b64 s[62:63], s[24:25]
	s_cbranch_execz .LBB0_676
	v_subrev_u32_e32 v180, s33, v173
	v_mov_b32_e32 v181, v1
	v_lshl_add_u64 v[180:181], v[176:177], 0, v[180:181]
	s_lshl_b64 s[6:7], s[52:53], 2
	v_lshl_add_u64 v[180:181], v[180:181], 1, v[0:1]
	s_add_u32 s6, s12, s6
	v_lshlrev_b64 v[180:181], s50, v[180:181]
	s_addc_u32 s7, s13, s7
	v_lshl_add_u64 v[180:181], v[180:181], 0, s[18:19]
	s_or_b64 s[64:65], s[0:1], exec

; __device__ __forceinline__ unsigned cvt_pk_bf16(float lo, float hi) { unsigned r; asm volatile("v_cvt_pk_bf16_f32 %0, %1, %2" : "=v"(r) : "v"(lo), "v"(hi)); return r; }
;     __device__ __forceinline__ void operator()(const f32x4 (&acc)[2][2][4][2], const pg8::Unit& u, int wr, int wc, int fr, int fq) const {
;     ...
;             for (int m = 0; m < 4; ++m) { const int row = row0 + ai * 128 + m * 16; const float rs = __builtin_amdgcn_rsqf(ss[row] * (1.f / DM) + EPS);
;                 f32x4 v[2][2]; float s = 0.f;
; #pragma unroll
;                 for (int bj = 0; bj < 2; ++bj)
; #pragma unroll
;                     for (int n = 0; n < 2; ++n) { v[bj][n] = acc[ai][bj][m][n] * rs; s += (v[bj][n][0] * v[bj][n][0] + v[bj][n][1] * v[bj][n][1]) + (v[bj][n][2] * v[bj][n][2] + v[bj][n][3] * v[bj][n][3]); }
;                 s += __shfl_xor(s, 16); s += __shfl_xor(s, 32);
;                 const float inv = (kind < 2) ? __builtin_amdgcn_rsqf(s * (1.f / 64.f) + EPS) : 1.f;
; #pragma unroll
;                 for (int bj = 0; bj < 2; ++bj)
; #pragma unroll
;                     for (int n = 0; n < 2; ++n) v[bj][n] = v[bj][n] * gv[bj][n] * inv;
;                 if (row < MPR) {
;                     const int b = row >> 11, sq = row & 2047, p = ((sq & (dil - 1)) << (11 - sh)) + (sq >> sh);
;                     bf16* dst = (bf16*)(wsb + boff) + ((size_t)(b * nh + idx) * 2048 + p) * 64;
; #pragma unroll
;                     for (int bj = 0; bj < 2; ++bj)
; #pragma unroll
;                         for (int n = 0; n < 2; ++n) { u32x2 w; w.x = cvt_pk_bf16(v[bj][n][0], v[bj][n][1]); w.y = cvt_pk_bf16(v[bj][n][2], v[bj][n][3]); *(u32x2*)(dst + 32 * bj + 16 * n + 4 * fq) = w; }
;                     if (kind > 0 && sq >= 2048 - win) {
.LBB0_687:
	s_or_saveexec_b64 s[4:5], s[4:5]
	s_waitcnt lgkmcnt(0)
	v_add_f32_e32 v173, v173, v175
	v_fmamk_f32 v173, v173, 0x3c800000, v236
	v_rsq_f32_e32 v173, v173
	v_pk_mul_f32 v[186:187], v[138:139], v[160:161]
	v_pk_mul_f32 v[158:159], v[140:141], v[158:159]
	v_pk_mul_f32 v[150:151], v[146:147], v[150:151]
	v_cndmask_b32_e64 v182, 1.0, v173, s[10:11]
	v_pk_mul_f32 v[152:153], v[148:149], v[152:153]
	v_pk_mul_f32 v[154:155], v[142:143], v[154:155]
	v_pk_mul_f32 v[156:157], v[144:145], v[156:157]
	v_pk_mul_f32 v[160:161], v[158:159], v[182:183] op_sel_hi:[1,0]
	v_pk_mul_f32 v[158:159], v[186:187], v[182:183] op_sel_hi:[1,0]
	v_pk_mul_f32 v[186:187], v[134:135], v[164:165]
	v_pk_mul_f32 v[162:163], v[136:137], v[162:163]
	v_pk_mul_f32 v[152:153], v[152:153], v[182:183] op_sel_hi:[1,0]
	v_pk_mul_f32 v[150:151], v[150:151], v[182:183] op_sel_hi:[1,0]
	v_pk_mul_f32 v[156:157], v[156:157], v[182:183] op_sel_hi:[1,0]
	v_pk_mul_f32 v[154:155], v[154:155], v[182:183] op_sel_hi:[1,0]
	v_pk_mul_f32 v[164:165], v[162:163], v[182:183] op_sel_hi:[1,0]
	v_pk_mul_f32 v[162:163], v[186:187], v[182:183] op_sel_hi:[1,0]
	v_mov_b64_e32 v[182:183], s[6:7]
	s_xor_b64 exec, exec, s[4:5]
	s_cbranch_execz .LBB0_691
	s_add_u32 s6, s14, s43
	s_addc_u32 s7, s15, 0
	v_and_b32_e32 v173, 0x7df, v167
	v_lshlrev_b32_e32 v167, s78, v167
	s_add_u32 s6, s6, s51
	v_and_b32_e32 v167, 0x7fe, v167
	v_lshrrev_b32_e32 v175, s41, v173
	s_addc_u32 s7, s7, 0
	v_lshl_add_u64 v[180:181], s[6:7], 0, v[178:179]
	v_add_lshl_u32 v182, v167, v175, 7
	v_mov_b32_e32 v183, v1
	v_lshl_add_u64 v[180:181], v[180:181], 0, v[182:183]
	v_mov_b32_e32 v175, v1
	v_lshl_add_u64 v[180:181], v[180:181], 0, v[174:175]
	v_cvt_pk_bf16_f32 v190, v150, v151
	v_cvt_pk_bf16_f32 v191, v152, v153
	v_cvt_pk_bf16_f32 v192, v154, v155
	v_cvt_pk_bf16_f32 v193, v156, v157
	v_cmp_le_i32_e32 vcc, s33, v173
	v_cvt_pk_bf16_f32 v194, v158, v159
	v_cvt_pk_bf16_f32 v195, v160, v161
	s_and_b64 s[24:25], s[54:55], vcc
	s_mov_b64 s[64:65], s[0:1]
	v_cvt_pk_bf16_f32 v196, v162, v163
	v_cvt_pk_bf16_f32 v197, v164, v165
	s_nop 1
	v_permlane16_swap_b32_e32 v190, v192
	v_permlane16_swap_b32_e32 v191, v193
	v_permlane16_swap_b32_e32 v194, v196
	v_permlane16_swap_b32_e32 v195, v197
	global_store_dwordx4 v[180:181], v[190:193], off
	global_store_dwordx4 v[180:181], v[194:197], off offset:64
	s_and_saveexec_b64 s[62:63], s[24:25]
	s_cbranch_execz .LBB0_690
	v_subrev_u32_e32 v180, s33, v173
	v_mov_b32_e32 v181, v1
	v_lshl_add_u64 v[180:181], v[176:177], 0, v[180:181]
	s_lshl_b64 s[6:7], s[52:53], 2
	v_lshl_add_u64 v[180:181], v[180:181], 1, v[0:1]
	s_add_u32 s6, s12, s6
	v_lshlrev_b64 v[180:181], s50, v[180:181]
	s_addc_u32 s7, s13, s7
	v_lshl_add_u64 v[180:181], v[180:181], 0, s[18:19]
	s_or_b64 s[64:65], s[0:1], exec

; __device__ __forceinline__ unsigned cvt_pk_bf16(float lo, float hi) { unsigned r; asm volatile("v_cvt_pk_bf16_f32 %0, %1, %2" : "=v"(r) : "v"(lo), "v"(hi)); return r; }
;     __device__ __forceinline__ void operator()(const f32x4 (&acc)[2][2][4][2], const pg8::Unit& u, int wr, int wc, int fr, int fq) const {
;     ...
;             for (int m = 0; m < 4; ++m) { const int row = row0 + ai * 128 + m * 16; const float rs = __builtin_amdgcn_rsqf(ss[row] * (1.f / DM) + EPS);
;                 f32x4 v[2][2]; float s = 0.f;
; #pragma unroll
;                 for (int bj = 0; bj < 2; ++bj)
; #pragma unroll
;                     for (int n = 0; n < 2; ++n) { v[bj][n] = acc[ai][bj][m][n] * rs; s += (v[bj][n][0] * v[bj][n][0] + v[bj][n][1] * v[bj][n][1]) + (v[bj][n][2] * v[bj][n][2] + v[bj][n][3] * v[bj][n][3]); }
;                 s += __shfl_xor(s, 16); s += __shfl_xor(s, 32);
;                 const float inv = (kind < 2) ? __builtin_amdgcn_rsqf(s * (1.f / 64.f) + EPS) : 1.f;
; #pragma unroll
;                 for (int bj = 0; bj < 2; ++bj)
; #pragma unroll
;                     for (int n = 0; n < 2; ++n) v[bj][n] = v[bj][n] * gv[bj][n] * inv;
;                 if (row < MPR) {
;                     const int b = row >> 11, sq = row & 2047, p = ((sq & (dil - 1)) << (11 - sh)) + (sq >> sh);
;                     bf16* dst = (bf16*)(wsb + boff) + ((size_t)(b * nh + idx) * 2048 + p) * 64;
; #pragma unroll
;                     for (int bj = 0; bj < 2; ++bj)
; #pragma unroll
;                         for (int n = 0; n < 2; ++n) { u32x2 w; w.x = cvt_pk_bf16(v[bj][n][0], v[bj][n][1]); w.y = cvt_pk_bf16(v[bj][n][2], v[bj][n][3]); *(u32x2*)(dst + 32 * bj + 16 * n + 4 * fq) = w; }
;                     if (kind > 0 && sq >= 2048 - win) {
.LBB0_701:
	s_or_saveexec_b64 s[4:5], s[4:5]
	s_waitcnt lgkmcnt(0)
	v_add_f32_e32 v173, v173, v175
	v_fmamk_f32 v173, v173, 0x3c800000, v236
	v_rsq_f32_e32 v173, v173
	v_pk_mul_f32 v[186:187], v[138:139], v[160:161]
	v_pk_mul_f32 v[158:159], v[140:141], v[158:159]
	v_pk_mul_f32 v[150:151], v[146:147], v[150:151]
	v_cndmask_b32_e64 v182, 1.0, v173, s[10:11]
	v_pk_mul_f32 v[152:153], v[148:149], v[152:153]
	v_pk_mul_f32 v[154:155], v[142:143], v[154:155]
	v_pk_mul_f32 v[156:157], v[144:145], v[156:157]
	v_pk_mul_f32 v[160:161], v[158:159], v[182:183] op_sel_hi:[1,0]
	v_pk_mul_f32 v[158:159], v[186:187], v[182:183] op_sel_hi:[1,0]
	v_pk_mul_f32 v[186:187], v[134:135], v[164:165]
	v_pk_mul_f32 v[162:163], v[136:137], v[162:163]
	v_pk_mul_f32 v[152:153], v[152:153], v[182:183] op_sel_hi:[1,0]
	v_pk_mul_f32 v[150:151], v[150:151], v[182:183] op_sel_hi:[1,0]
	v_pk_mul_f32 v[156:157], v[156:157], v[182:183] op_sel_hi:[1,0]
	v_pk_mul_f32 v[154:155], v[154:155], v[182:183] op_sel_hi:[1,0]
	v_pk_mul_f32 v[164:165], v[162:163], v[182:183] op_sel_hi:[1,0]
	v_pk_mul_f32 v[162:163], v[186:187], v[182:183] op_sel_hi:[1,0]
	v_mov_b64_e32 v[182:183], s[6:7]
	s_xor_b64 exec, exec, s[4:5]
	s_cbranch_execz .LBB0_705
	s_add_u32 s6, s14, s43
	s_addc_u32 s7, s15, 0
	v_and_b32_e32 v173, 0x7ef, v167
	v_lshlrev_b32_e32 v167, s78, v167
	s_add_u32 s6, s6, s51
	v_and_b32_e32 v167, 0x7fe, v167
	v_lshrrev_b32_e32 v175, s41, v173
	s_addc_u32 s7, s7, 0
	v_lshl_add_u64 v[180:181], s[6:7], 0, v[178:179]
	v_add_lshl_u32 v182, v167, v175, 7
	v_mov_b32_e32 v183, v1
	v_lshl_add_u64 v[180:181], v[180:181], 0, v[182:183]
	v_mov_b32_e32 v175, v1
	v_lshl_add_u64 v[180:181], v[180:181], 0, v[174:175]
	v_cvt_pk_bf16_f32 v190, v150, v151
	v_cvt_pk_bf16_f32 v191, v152, v153
	v_cvt_pk_bf16_f32 v192, v154, v155
	v_cvt_pk_bf16_f32 v193, v156, v157
	v_cmp_le_i32_e32 vcc, s33, v173
	v_cvt_pk_bf16_f32 v194, v158, v159
	v_cvt_pk_bf16_f32 v195, v160, v161
	s_and_b64 s[24:25], s[54:55], vcc
	s_mov_b64 s[64:65], s[0:1]
	v_cvt_pk_bf16_f32 v196, v162, v163
	v_cvt_pk_bf16_f32 v197, v164, v165
	s_nop 1
	v_permlane16_swap_b32_e32 v190, v192
	v_permlane16_swap_b32_e32 v191, v193
	v_permlane16_swap_b32_e32 v194, v196
	v_permlane16_swap_b32_e32 v195, v197
	global_store_dwordx4 v[180:181], v[190:193], off
	global_store_dwordx4 v[180:181], v[194:197], off offset:64
	s_and_saveexec_b64 s[62:63], s[24:25]
	s_cbranch_execz .LBB0_704
	v_subrev_u32_e32 v180, s33, v173
	v_mov_b32_e32 v181, v1
	v_lshl_add_u64 v[180:181], v[176:177], 0, v[180:181]
	s_lshl_b64 s[6:7], s[52:53], 2
	v_lshl_add_u64 v[180:181], v[180:181], 1, v[0:1]
	s_add_u32 s6, s12, s6
	v_lshlrev_b64 v[180:181], s50, v[180:181]
	s_addc_u32 s7, s13, s7
	v_lshl_add_u64 v[180:181], v[180:181], 0, s[18:19]
	s_or_b64 s[64:65], s[0:1], exec

; __device__ __forceinline__ unsigned cvt_pk_bf16(float lo, float hi) { unsigned r; asm volatile("v_cvt_pk_bf16_f32 %0, %1, %2" : "=v"(r) : "v"(lo), "v"(hi)); return r; }
;     __device__ __forceinline__ void operator()(const f32x4 (&acc)[2][2][4][2], const pg8::Unit& u, int wr, int wc, int fr, int fq) const {
;     ...
;             for (int m = 0; m < 4; ++m) { const int row = row0 + ai * 128 + m * 16; const float rs = __builtin_amdgcn_rsqf(ss[row] * (1.f / DM) + EPS);
;                 f32x4 v[2][2]; float s = 0.f;
; #pragma unroll
;                 for (int bj = 0; bj < 2; ++bj)
; #pragma unroll
;                     for (int n = 0; n < 2; ++n) { v[bj][n] = acc[ai][bj][m][n] * rs; s += (v[bj][n][0] * v[bj][n][0] + v[bj][n][1] * v[bj][n][1]) + (v[bj][n][2] * v[bj][n][2] + v[bj][n][3] * v[bj][n][3]); }
;                 s += __shfl_xor(s, 16); s += __shfl_xor(s, 32);
;                 const float inv = (kind < 2) ? __builtin_amdgcn_rsqf(s * (1.f / 64.f) + EPS) : 1.f;
; #pragma unroll
;                 for (int bj = 0; bj < 2; ++bj)
; #pragma unroll
;                     for (int n = 0; n < 2; ++n) v[bj][n] = v[bj][n] * gv[bj][n] * inv;
;                 if (row < MPR) {
;                     const int b = row >> 11, sq = row & 2047, p = ((sq & (dil - 1)) << (11 - sh)) + (sq >> sh);
;                     bf16* dst = (bf16*)(wsb + boff) + ((size_t)(b * nh + idx) * 2048 + p) * 64;
; #pragma unroll
;                     for (int bj = 0; bj < 2; ++bj)
; #pragma unroll
;                         for (int n = 0; n < 2; ++n) { u32x2 w; w.x = cvt_pk_bf16(v[bj][n][0], v[bj][n][1]); w.y = cvt_pk_bf16(v[bj][n][2], v[bj][n][3]); *(u32x2*)(dst + 32 * bj + 16 * n + 4 * fq) = w; }
;                     if (kind > 0 && sq >= 2048 - win) {
.LBB0_715:
	s_or_saveexec_b64 s[4:5], s[4:5]
	s_waitcnt lgkmcnt(0)
	v_add_f32_e32 v168, v173, v175
	v_fmamk_f32 v168, v168, 0x3c800000, v236
	v_rsq_f32_e32 v168, v168
	v_pk_mul_f32 v[146:147], v[146:147], v[150:151]
	v_pk_mul_f32 v[148:149], v[148:149], v[152:153]
	v_pk_mul_f32 v[142:143], v[142:143], v[154:155]
	v_cndmask_b32_e64 v150, 1.0, v168, s[10:11]
	v_pk_mul_f32 v[144:145], v[144:145], v[156:157]
	v_pk_mul_f32 v[138:139], v[138:139], v[160:161]
	v_pk_mul_f32 v[140:141], v[140:141], v[158:159]
	v_pk_mul_f32 v[134:135], v[134:135], v[164:165]
	v_pk_mul_f32 v[136:137], v[136:137], v[162:163]
	v_pk_mul_f32 v[148:149], v[148:149], v[150:151] op_sel_hi:[1,0]
	v_pk_mul_f32 v[146:147], v[146:147], v[150:151] op_sel_hi:[1,0]
	v_pk_mul_f32 v[144:145], v[144:145], v[150:151] op_sel_hi:[1,0]
	v_pk_mul_f32 v[142:143], v[142:143], v[150:151] op_sel_hi:[1,0]
	v_pk_mul_f32 v[140:141], v[140:141], v[150:151] op_sel_hi:[1,0]
	v_pk_mul_f32 v[138:139], v[138:139], v[150:151] op_sel_hi:[1,0]
	v_pk_mul_f32 v[136:137], v[136:137], v[150:151] op_sel_hi:[1,0]
	v_pk_mul_f32 v[134:135], v[134:135], v[150:151] op_sel_hi:[1,0]
	v_mov_b64_e32 v[150:151], s[6:7]
	s_xor_b64 exec, exec, s[4:5]
	s_cbranch_execz .LBB0_719
	s_add_u32 s3, s14, s43
	s_addc_u32 s7, s15, 0
	v_and_b32_e32 v150, 0x7ff, v167
	v_lshlrev_b32_e32 v151, s78, v167
	s_add_u32 s6, s3, s51
	v_and_b32_e32 v151, 0x7fe, v151
	v_lshrrev_b32_e32 v154, s41, v150
	s_addc_u32 s7, s7, 0
	v_lshl_add_u64 v[152:153], s[6:7], 0, v[178:179]
	v_add_lshl_u32 v154, v151, v154, 7
	v_mov_b32_e32 v155, v1
	v_lshl_add_u64 v[152:153], v[152:153], 0, v[154:155]
	v_mov_b32_e32 v175, v1
	v_lshl_add_u64 v[152:153], v[152:153], 0, v[174:175]
	v_cvt_pk_bf16_f32 v190, v146, v147
	v_cvt_pk_bf16_f32 v191, v148, v149
	v_cvt_pk_bf16_f32 v192, v142, v143
	v_cvt_pk_bf16_f32 v193, v144, v145
	v_cmp_le_i32_e32 vcc, s33, v150
	v_cvt_pk_bf16_f32 v194, v138, v139
	v_cvt_pk_bf16_f32 v195, v140, v141
	s_and_b64 s[24:25], s[54:55], vcc
	s_mov_b64 s[54:55], s[0:1]
	v_cvt_pk_bf16_f32 v196, v134, v135
	v_cvt_pk_bf16_f32 v197, v136, v137
	s_nop 1
	v_permlane16_swap_b32_e32 v190, v192
	v_permlane16_swap_b32_e32 v191, v193
	v_permlane16_swap_b32_e32 v194, v196
	v_permlane16_swap_b32_e32 v195, v197
	global_store_dwordx4 v[152:153], v[190:193], off
	global_store_dwordx4 v[152:153], v[194:197], off offset:64
	s_and_saveexec_b64 s[10:11], s[24:25]
	s_cbranch_execz .LBB0_718
	v_subrev_u32_e32 v150, s33, v150
	v_mov_b32_e32 v151, v1
	v_lshl_add_u64 v[150:151], v[176:177], 0, v[150:151]
	s_lshl_b64 s[6:7], s[52:53], 2
	v_lshl_add_u64 v[150:151], v[150:151], 1, v[0:1]
	s_add_u32 s6, s12, s6
	v_lshlrev_b64 v[150:151], s50, v[150:151]
	s_addc_u32 s7, s13, s7
	v_lshl_add_u64 v[170:171], v[150:151], 0, s[18:19]
	s_or_b64 s[54:55], s[0:1], exec
